# in-proj V^T and F^T epilogues rewritten by hand (SGPR-base store addresses, paired token packing; about half the instructions)
# speedup vs baseline: 1.0064x; 1.0002x over previous
.LBB0_145:
	s_add_u32 s6, s2, 0xfffc0080
	s_addc_u32 s7, s3, -1
	s_add_i32 s29, 0, 0x10000
	s_cmp_eq_u32 s28, 12
	s_cselect_b32 s11, s9, s7
	s_cselect_b32 s10, s12, s6
	s_cselect_b32 s7, s13, s27
	s_cselect_b32 s6, s17, s19
	v_lshl_add_u64 v[190:191], s[2:3], 0, v[154:155]
	s_add_i32 m0, s50, 0xc000
	ds_read_b128 v[170:173], v216
	ds_read_b128 v[178:181], v216 offset:2048
	ds_read_b128 v[186:189], v216 offset:4096
	ds_read_b128 v[222:225], v216 offset:6144
	ds_read_b128 v[174:177], v216 offset:1024
	ds_read_b128 v[182:185], v216 offset:3072
	ds_read_b128 v[218:221], v216 offset:5120
	ds_read_b128 v[226:229], v216 offset:7168
	global_load_lds_dwordx4 v[190:191], off
	v_lshl_add_u64 v[190:191], s[2:3], 0, v[156:157]
	s_add_i32 m0, s50, 0xe000
	s_nop 0
	global_load_lds_dwordx4 v[190:191], off
	s_waitcnt lgkmcnt(8)
	s_waitcnt vmcnt(10)
	s_barrier
	s_waitcnt lgkmcnt(4)
	s_setprio 1
	v_mfma_f32_16x16x32_bf16 v[124:127], v[128:131], v[170:173], v[124:127]
	v_mfma_f32_16x16x32_bf16 v[120:123], v[162:165], v[170:173], v[120:123]
	v_mfma_f32_16x16x32_bf16 v[108:111], v[128:131], v[178:181], v[108:111]
	v_mfma_f32_16x16x32_bf16 v[104:107], v[162:165], v[178:181], v[104:107]
	v_mfma_f32_16x16x32_bf16 v[92:95], v[128:131], v[186:189], v[92:95]
	v_mfma_f32_16x16x32_bf16 v[88:91], v[162:165], v[186:189], v[88:91]
	v_mfma_f32_16x16x32_bf16 v[76:79], v[128:131], v[222:225], v[76:79]
	v_mfma_f32_16x16x32_bf16 v[72:75], v[162:165], v[222:225], v[72:75]
	s_waitcnt lgkmcnt(0)
	v_mfma_f32_16x16x32_bf16 v[124:127], v[158:161], v[174:177], v[124:127]
	v_mfma_f32_16x16x32_bf16 v[120:123], v[166:169], v[174:177], v[120:123]
	v_mfma_f32_16x16x32_bf16 v[108:111], v[158:161], v[182:185], v[108:111]
	v_mfma_f32_16x16x32_bf16 v[104:107], v[166:169], v[182:185], v[104:107]
	v_mfma_f32_16x16x32_bf16 v[92:95], v[158:161], v[218:221], v[92:95]
	v_mfma_f32_16x16x32_bf16 v[88:91], v[166:169], v[218:221], v[88:91]
	v_mfma_f32_16x16x32_bf16 v[76:79], v[158:161], v[226:229], v[76:79]
	v_mfma_f32_16x16x32_bf16 v[72:75], v[166:169], v[226:229], v[72:75]
	s_setprio 0
	s_barrier
	s_add_i32 s34, 0, 0x14000
	s_add_i32 s29, s29, s15
	v_add_u32_e32 v132, s34, v215
	v_lshl_add_u64 v[190:191], s[6:7], 0, v[150:151]
	s_mov_b32 m0, s29
	ds_read_b128 v[230:233], v132
	ds_read_b128 v[238:241], v132 offset:2048
	ds_read_b128 v[234:237], v132 offset:1024
	ds_read_b128 v[242:245], v132 offset:3072
	global_load_lds_dwordx4 v[190:191], off
	v_lshl_add_u64 v[246:247], s[6:7], 0, v[152:153]
	s_add_i32 m0, s29, 0x2000
	s_nop 0
	global_load_lds_dwordx4 v[246:247], off
	s_waitcnt vmcnt(10)
	s_barrier
	s_waitcnt lgkmcnt(2)
	s_setprio 1
	v_mfma_f32_16x16x32_bf16 v[116:119], v[230:233], v[170:173], v[116:119]
	v_mfma_f32_16x16x32_bf16 v[112:115], v[238:241], v[170:173], v[112:115]
	v_mfma_f32_16x16x32_bf16 v[100:103], v[230:233], v[178:181], v[100:103]
	v_mfma_f32_16x16x32_bf16 v[96:99], v[238:241], v[178:181], v[96:99]
	v_mfma_f32_16x16x32_bf16 v[84:87], v[230:233], v[186:189], v[84:87]
	v_mfma_f32_16x16x32_bf16 v[80:83], v[238:241], v[186:189], v[80:83]
	v_mfma_f32_16x16x32_bf16 v[68:71], v[230:233], v[222:225], v[68:71]
	v_mfma_f32_16x16x32_bf16 v[64:67], v[238:241], v[222:225], v[64:67]
	s_waitcnt lgkmcnt(0)
	v_mfma_f32_16x16x32_bf16 v[116:119], v[234:237], v[174:177], v[116:119]
	v_mfma_f32_16x16x32_bf16 v[112:115], v[242:245], v[174:177], v[112:115]
	v_mfma_f32_16x16x32_bf16 v[100:103], v[234:237], v[182:185], v[100:103]
	v_mfma_f32_16x16x32_bf16 v[96:99], v[242:245], v[182:185], v[96:99]
	v_mfma_f32_16x16x32_bf16 v[84:87], v[234:237], v[218:221], v[84:87]
	v_mfma_f32_16x16x32_bf16 v[80:83], v[242:245], v[218:221], v[80:83]
	v_mfma_f32_16x16x32_bf16 v[68:71], v[234:237], v[226:229], v[68:71]
	v_mfma_f32_16x16x32_bf16 v[64:67], v[242:245], v[226:229], v[64:67]
	s_setprio 0
	s_mov_b32 m0, s50
	v_lshl_add_u64 v[248:249], s[10:11], 0, v[150:151]
	s_barrier
	ds_read_b128 v[170:173], v216 offset:16384
	ds_read_b128 v[178:181], v216 offset:18432
	ds_read_b128 v[186:189], v216 offset:20480
	ds_read_b128 v[222:225], v216 offset:22528
	ds_read_b128 v[174:177], v216 offset:17408
	ds_read_b128 v[182:185], v216 offset:19456
	ds_read_b128 v[218:221], v216 offset:21504
	ds_read_b128 v[226:229], v216 offset:23552
	global_load_lds_dwordx4 v[248:249], off
	v_lshl_add_u64 v[250:251], s[10:11], 0, v[152:153]
	s_mov_b32 m0, s51
	s_nop 0
	global_load_lds_dwordx4 v[250:251], off
	s_waitcnt vmcnt(10)
	s_barrier
	s_waitcnt lgkmcnt(4)
	s_setprio 1
	v_mfma_f32_16x16x32_bf16 v[60:63], v[128:131], v[170:173], v[60:63]
	v_mfma_f32_16x16x32_bf16 v[56:59], v[162:165], v[170:173], v[56:59]
	v_mfma_f32_16x16x32_bf16 v[44:47], v[128:131], v[178:181], v[44:47]
	v_mfma_f32_16x16x32_bf16 v[40:43], v[162:165], v[178:181], v[40:43]
	v_mfma_f32_16x16x32_bf16 v[28:31], v[128:131], v[186:189], v[28:31]
	v_mfma_f32_16x16x32_bf16 v[24:27], v[162:165], v[186:189], v[24:27]
	v_mfma_f32_16x16x32_bf16 v[12:15], v[128:131], v[222:225], v[12:15]
	v_mfma_f32_16x16x32_bf16 v[8:11], v[162:165], v[222:225], v[8:11]
	s_waitcnt lgkmcnt(0)
	v_mfma_f32_16x16x32_bf16 v[60:63], v[158:161], v[174:177], v[60:63]
	v_mfma_f32_16x16x32_bf16 v[56:59], v[166:169], v[174:177], v[56:59]
	v_mfma_f32_16x16x32_bf16 v[44:47], v[158:161], v[182:185], v[44:47]
	v_mfma_f32_16x16x32_bf16 v[40:43], v[166:169], v[182:185], v[40:43]
	v_mfma_f32_16x16x32_bf16 v[28:31], v[158:161], v[218:221], v[28:31]
	v_mfma_f32_16x16x32_bf16 v[24:27], v[166:169], v[218:221], v[24:27]
	v_mfma_f32_16x16x32_bf16 v[12:15], v[158:161], v[226:229], v[12:15]
	v_mfma_f32_16x16x32_bf16 v[8:11], v[166:169], v[226:229], v[8:11]
	s_setprio 0
	s_barrier
	s_add_u32 s30, s6, 0x40000
	s_addc_u32 s31, s7, 0
	s_add_i32 s29, s34, s15
	v_lshl_add_u64 v[128:129], s[30:31], 0, v[150:151]
	s_mov_b32 m0, s29
	s_nop 0
	global_load_lds_dwordx4 v[128:129], off
	v_lshl_add_u64 v[128:129], s[30:31], 0, v[152:153]
	s_add_i32 m0, s29, 0x2000
	s_nop 0
	global_load_lds_dwordx4 v[128:129], off
	v_add_u32_e32 v166, 0x18000, v215
	ds_read_b128 v[128:131], v166
	ds_read_b128 v[158:161], v166 offset:1024
	ds_read_b128 v[162:165], v166 offset:2048
	ds_read_b128 v[166:169], v166 offset:3072
	s_waitcnt vmcnt(10)
	s_barrier
	s_setprio 1
	v_mfma_f32_16x16x32_bf16 v[52:55], v[230:233], v[170:173], v[52:55]
	v_mfma_f32_16x16x32_bf16 v[48:51], v[238:241], v[170:173], v[48:51]
	v_mfma_f32_16x16x32_bf16 v[36:39], v[230:233], v[178:181], v[36:39]
	v_mfma_f32_16x16x32_bf16 v[32:35], v[238:241], v[178:181], v[32:35]
	v_mfma_f32_16x16x32_bf16 v[20:23], v[230:233], v[186:189], v[20:23]
	v_mfma_f32_16x16x32_bf16 v[16:19], v[238:241], v[186:189], v[16:19]
	v_mfma_f32_16x16x32_bf16 v[4:7], v[230:233], v[222:225], v[4:7]
	v_mfma_f32_16x16x32_bf16 v[0:3], v[238:241], v[222:225], v[0:3]
	v_mfma_f32_16x16x32_bf16 v[52:55], v[234:237], v[174:177], v[52:55]
	v_mfma_f32_16x16x32_bf16 v[48:51], v[242:245], v[174:177], v[48:51]
	v_mfma_f32_16x16x32_bf16 v[36:39], v[234:237], v[182:185], v[36:39]
	v_mfma_f32_16x16x32_bf16 v[32:35], v[242:245], v[182:185], v[32:35]
	v_mfma_f32_16x16x32_bf16 v[20:23], v[234:237], v[218:221], v[20:23]
	v_mfma_f32_16x16x32_bf16 v[16:19], v[242:245], v[218:221], v[16:19]
	v_mfma_f32_16x16x32_bf16 v[4:7], v[234:237], v[226:229], v[4:7]
	v_mfma_f32_16x16x32_bf16 v[0:3], v[242:245], v[226:229], v[0:3]
	s_setprio 0
	s_add_i32 s29, 0, 0x18000
	s_barrier
	s_add_u32 s10, s10, 0x40000
	s_addc_u32 s11, s11, 0
	s_mov_b32 m0, s36
	v_lshl_add_u64 v[230:231], s[10:11], 0, v[150:151]
	ds_read_b128 v[170:173], v216 offset:32768
	ds_read_b128 v[178:181], v216 offset:34816
	ds_read_b128 v[186:189], v216 offset:36864
	ds_read_b128 v[222:225], v216 offset:38912
	ds_read_b128 v[174:177], v216 offset:33792
	ds_read_b128 v[182:185], v216 offset:35840
	ds_read_b128 v[218:221], v216 offset:37888
	ds_read_b128 v[226:229], v216 offset:39936
	global_load_lds_dwordx4 v[230:231], off
	v_lshl_add_u64 v[230:231], s[10:11], 0, v[152:153]
	s_mov_b32 m0, s37
	s_nop 0
	global_load_lds_dwordx4 v[230:231], off
	s_waitcnt lgkmcnt(8)
	s_waitcnt vmcnt(10)
	s_barrier
	s_waitcnt lgkmcnt(4)
	s_setprio 1
	v_mfma_f32_16x16x32_bf16 v[124:127], v[128:131], v[170:173], v[124:127]
	v_mfma_f32_16x16x32_bf16 v[120:123], v[162:165], v[170:173], v[120:123]
	v_mfma_f32_16x16x32_bf16 v[108:111], v[128:131], v[178:181], v[108:111]
	v_mfma_f32_16x16x32_bf16 v[104:107], v[162:165], v[178:181], v[104:107]
	v_mfma_f32_16x16x32_bf16 v[92:95], v[128:131], v[186:189], v[92:95]
	v_mfma_f32_16x16x32_bf16 v[88:91], v[162:165], v[186:189], v[88:91]
	v_mfma_f32_16x16x32_bf16 v[76:79], v[128:131], v[222:225], v[76:79]
	v_mfma_f32_16x16x32_bf16 v[72:75], v[162:165], v[222:225], v[72:75]
	s_waitcnt lgkmcnt(0)
	v_mfma_f32_16x16x32_bf16 v[124:127], v[158:161], v[174:177], v[124:127]
	v_mfma_f32_16x16x32_bf16 v[120:123], v[166:169], v[174:177], v[120:123]
	v_mfma_f32_16x16x32_bf16 v[108:111], v[158:161], v[182:185], v[108:111]
	v_mfma_f32_16x16x32_bf16 v[104:107], v[166:169], v[182:185], v[104:107]
	v_mfma_f32_16x16x32_bf16 v[92:95], v[158:161], v[218:221], v[92:95]
	v_mfma_f32_16x16x32_bf16 v[88:91], v[166:169], v[218:221], v[88:91]
	v_mfma_f32_16x16x32_bf16 v[76:79], v[158:161], v[226:229], v[76:79]
	v_mfma_f32_16x16x32_bf16 v[72:75], v[166:169], v[226:229], v[72:75]
	s_setprio 0
	s_barrier
	s_add_i32 s10, 0, 0x1c000
	s_add_i32 s11, s29, s15
	v_add_u32_e32 v132, s10, v215
	v_lshl_add_u64 v[190:191], v[190:191], 0, s[66:67]
	s_mov_b32 m0, s11
	ds_read_b128 v[230:233], v132
	ds_read_b128 v[238:241], v132 offset:2048
	ds_read_b128 v[234:237], v132 offset:1024
	ds_read_b128 v[242:245], v132 offset:3072
	global_load_lds_dwordx4 v[190:191], off
	v_lshl_add_u64 v[190:191], v[246:247], 0, s[66:67]
	s_add_i32 m0, s11, 0x2000
	s_nop 0
	global_load_lds_dwordx4 v[190:191], off
	s_waitcnt vmcnt(10)
	s_barrier
	s_waitcnt lgkmcnt(2)
	s_setprio 1
	v_mfma_f32_16x16x32_bf16 v[116:119], v[230:233], v[170:173], v[116:119]
	v_mfma_f32_16x16x32_bf16 v[112:115], v[238:241], v[170:173], v[112:115]
	v_mfma_f32_16x16x32_bf16 v[100:103], v[230:233], v[178:181], v[100:103]
	v_mfma_f32_16x16x32_bf16 v[96:99], v[238:241], v[178:181], v[96:99]
	v_mfma_f32_16x16x32_bf16 v[84:87], v[230:233], v[186:189], v[84:87]
	v_mfma_f32_16x16x32_bf16 v[80:83], v[238:241], v[186:189], v[80:83]
	v_mfma_f32_16x16x32_bf16 v[68:71], v[230:233], v[222:225], v[68:71]
	v_mfma_f32_16x16x32_bf16 v[64:67], v[238:241], v[222:225], v[64:67]
	s_waitcnt lgkmcnt(0)
	v_mfma_f32_16x16x32_bf16 v[116:119], v[234:237], v[174:177], v[116:119]
	v_mfma_f32_16x16x32_bf16 v[112:115], v[242:245], v[174:177], v[112:115]
	v_mfma_f32_16x16x32_bf16 v[100:103], v[234:237], v[182:185], v[100:103]
	v_mfma_f32_16x16x32_bf16 v[96:99], v[242:245], v[182:185], v[96:99]
	v_mfma_f32_16x16x32_bf16 v[84:87], v[234:237], v[218:221], v[84:87]
	v_mfma_f32_16x16x32_bf16 v[80:83], v[242:245], v[218:221], v[80:83]
	v_mfma_f32_16x16x32_bf16 v[68:71], v[234:237], v[226:229], v[68:71]
	v_mfma_f32_16x16x32_bf16 v[64:67], v[242:245], v[226:229], v[64:67]
	s_setprio 0
	s_mov_b32 m0, s52
	v_lshl_add_u64 v[190:191], v[248:249], 0, s[66:67]
	s_barrier
	ds_read_b128 v[170:173], v216 offset:49152
	ds_read_b128 v[178:181], v216 offset:51200
	ds_read_b128 v[186:189], v216 offset:53248
	ds_read_b128 v[222:225], v216 offset:55296
	ds_read_b128 v[174:177], v216 offset:50176
	ds_read_b128 v[182:185], v216 offset:52224
	ds_read_b128 v[218:221], v216 offset:54272
	ds_read_b128 v[226:229], v216 offset:56320
	global_load_lds_dwordx4 v[190:191], off
	v_lshl_add_u64 v[190:191], v[250:251], 0, s[66:67]
	s_mov_b32 m0, s53
	s_nop 0
	global_load_lds_dwordx4 v[190:191], off
	s_waitcnt vmcnt(10)
	s_barrier
	s_waitcnt lgkmcnt(4)
	s_setprio 1
	v_mfma_f32_16x16x32_bf16 v[60:63], v[128:131], v[170:173], v[60:63]
	v_mfma_f32_16x16x32_bf16 v[56:59], v[162:165], v[170:173], v[56:59]
	v_mfma_f32_16x16x32_bf16 v[44:47], v[128:131], v[178:181], v[44:47]
	v_mfma_f32_16x16x32_bf16 v[40:43], v[162:165], v[178:181], v[40:43]
	v_mfma_f32_16x16x32_bf16 v[28:31], v[128:131], v[186:189], v[28:31]
	v_mfma_f32_16x16x32_bf16 v[24:27], v[162:165], v[186:189], v[24:27]
	v_mfma_f32_16x16x32_bf16 v[12:15], v[128:131], v[222:225], v[12:15]
	v_mfma_f32_16x16x32_bf16 v[8:11], v[162:165], v[222:225], v[8:11]
	s_waitcnt lgkmcnt(0)
	v_mfma_f32_16x16x32_bf16 v[60:63], v[158:161], v[174:177], v[60:63]
	v_mfma_f32_16x16x32_bf16 v[56:59], v[166:169], v[174:177], v[56:59]
	v_mfma_f32_16x16x32_bf16 v[44:47], v[158:161], v[182:185], v[44:47]
	v_mfma_f32_16x16x32_bf16 v[40:43], v[166:169], v[182:185], v[40:43]
	v_mfma_f32_16x16x32_bf16 v[28:31], v[158:161], v[218:221], v[28:31]
	v_mfma_f32_16x16x32_bf16 v[24:27], v[166:169], v[218:221], v[24:27]
	v_mfma_f32_16x16x32_bf16 v[12:15], v[158:161], v[226:229], v[12:15]
	v_mfma_f32_16x16x32_bf16 v[8:11], v[166:169], v[226:229], v[8:11]
	s_setprio 0
	s_barrier
	s_add_u32 s6, s6, 0x40080
	s_addc_u32 s7, s7, 0
	s_add_i32 s10, s10, s15
	v_lshl_add_u64 v[128:129], s[6:7], 0, v[150:151]
	s_mov_b32 m0, s10
	s_nop 0
	global_load_lds_dwordx4 v[128:129], off
	v_lshl_add_u64 v[128:129], s[6:7], 0, v[152:153]
	s_add_i32 m0, s10, 0x2000
	s_nop 0
	global_load_lds_dwordx4 v[128:129], off
	v_add_u32_e32 v166, 0x10000, v215
	ds_read_b128 v[128:131], v166
	ds_read_b128 v[158:161], v166 offset:1024
	ds_read_b128 v[162:165], v166 offset:2048
	ds_read_b128 v[166:169], v166 offset:3072
	s_waitcnt vmcnt(10)
	s_barrier
	s_setprio 1
	v_mfma_f32_16x16x32_bf16 v[52:55], v[230:233], v[170:173], v[52:55]
	v_mfma_f32_16x16x32_bf16 v[48:51], v[238:241], v[170:173], v[48:51]
	v_mfma_f32_16x16x32_bf16 v[36:39], v[230:233], v[178:181], v[36:39]
	v_mfma_f32_16x16x32_bf16 v[32:35], v[238:241], v[178:181], v[32:35]
	v_mfma_f32_16x16x32_bf16 v[20:23], v[230:233], v[186:189], v[20:23]
	v_mfma_f32_16x16x32_bf16 v[16:19], v[238:241], v[186:189], v[16:19]
	v_mfma_f32_16x16x32_bf16 v[4:7], v[230:233], v[222:225], v[4:7]
	v_mfma_f32_16x16x32_bf16 v[0:3], v[238:241], v[222:225], v[0:3]
	v_mfma_f32_16x16x32_bf16 v[52:55], v[234:237], v[174:177], v[52:55]
	v_mfma_f32_16x16x32_bf16 v[48:51], v[242:245], v[174:177], v[48:51]
	v_mfma_f32_16x16x32_bf16 v[36:39], v[234:237], v[182:185], v[36:39]
	v_mfma_f32_16x16x32_bf16 v[32:35], v[242:245], v[182:185], v[32:35]
	v_mfma_f32_16x16x32_bf16 v[20:23], v[234:237], v[218:221], v[20:23]
	v_mfma_f32_16x16x32_bf16 v[16:19], v[242:245], v[218:221], v[16:19]
	v_mfma_f32_16x16x32_bf16 v[4:7], v[234:237], v[226:229], v[4:7]
	v_mfma_f32_16x16x32_bf16 v[0:3], v[242:245], v[226:229], v[0:3]
	s_setprio 0
	s_add_i32 s28, s28, 2
	s_add_u32 s2, s2, 0x100
	s_addc_u32 s3, s3, 0
	s_add_u32 s19, s19, 0x100
	s_addc_u32 s27, s27, 0
	s_cmp_gt_u32 s28, 13
	s_barrier
	s_cbranch_scc0 .LBB0_145
	s_waitcnt lgkmcnt(0)
	v_mov_b32_e32 v166, v135
	s_mov_b64 s[2:3], s[0:1]
	v_readfirstlane_b32 s27, v166
	s_bfe_u32 s19, s27, 0x20006
	s_load_dwordx2 s[30:31], s[2:3], 0x88
	s_mov_b64 s[2:3], s[0:1]
	s_cmp_gt_i32 s8, 31
	s_load_dwordx2 s[28:29], s[2:3], 0x80
	s_cselect_b64 s[6:7], -1, 0
	s_cmp_lt_i32 s8, 32
	s_cselect_b64 s[2:3], -1, 0
	s_ashr_i32 s9, s27, 2
	s_lshl_b32 s8, s8, 8
	s_and_b32 s17, s9, 0xffffffc0
	v_and_b32_e32 v217, 15, v166
	s_add_i32 s17, s17, s8
	v_bfe_u32 v186, v166, 4, 2
	v_or_b32_e32 v158, s17, v217
	s_cmp_gt_i32 s26, 3
	s_mov_b64 s[8:9], -1
	s_cbranch_scc0 .LBB0_829
	s_cmp_gt_u32 s26, 5
	s_cbranch_scc0 .LBB0_409
	s_cmp_gt_u32 s26, 8
	s_cbranch_scc0 .LBB0_406
	s_waitcnt lgkmcnt(0)
	v_and_b32_e32 v128, 1, v166
	v_cmp_eq_u32_e64 s[8:9], 0, v128
	v_cmp_eq_u32_e32 vcc, 1, v128
	s_mov_b32 s10, 0x05040100
	s_mov_b32 s11, 0x07060302
	s_cmp_eq_u32 s6, 0
	s_cbranch_scc1 .Lvf_f_c
.Lvf_f_l:
	v_lshlrev_b32_e32 v129, 2, v186
	v_lshl_add_u32 v129, v128, 1, v129
	v_sub_u32_e32 v130, v217, v128
	v_lshlrev_b32_e32 v130, 1, v130
	v_mul_u32_u24_e32 v129, 0x1000, v129
	v_add_u32_e32 v248, v129, v130
	v_add_u32_e32 v249, 0x1000, v248
	s_lshr_b32 s58, s17, 8
	s_add_i32 s38, s26, -9
	s_lshl_b32 s38, s38, 22
	s_add_i32 s34, s58, 0xffffffe0
	s_lshr_b32 s34, s34, 3
	s_lshl_b32 s34, s34, 20
	s_add_i32 s38, s38, s34
	s_lshl_b32 s34, s19, 17
	s_add_i32 s38, s38, s34
	s_and_b32 s34, s58, 7
	s_lshl_b32 s34, s34, 8
	s_and_b32 s35, s17, 0xff
	s_add_i32 s34, s34, s35
	s_lshl_b32 s34, s34, 1
	s_add_i32 s38, s38, s34
	s_add_u32 s12, s30, s38
	s_addc_u32 s13, s31, 0
	s_add_u32 s12, s12, 0xeea4400
	s_addc_u32 s13, s13, 0
	v_cvt_pk_bf16_f32 v218, v124, v125
	v_cvt_pk_bf16_f32 v219, v126, v127
	v_cvt_pk_bf16_f32 v220, v120, v121
	v_cvt_pk_bf16_f32 v221, v122, v123
	v_cndmask_b32_e64 v222, v218, v219, s[8:9]
	v_cndmask_b32_e64 v223, v220, v221, s[8:9]
	s_nop 0
	v_mov_b32_dpp v222, v222 quad_perm:[1,0,3,2] row_mask:0xf bank_mask:0xf bound_ctrl:1
	v_mov_b32_dpp v223, v223 quad_perm:[1,0,3,2] row_mask:0xf bank_mask:0xf bound_ctrl:1
	v_cndmask_b32_e32 v224, v218, v222, vcc
	v_cndmask_b32_e32 v225, v222, v219, vcc
	v_cndmask_b32_e32 v226, v220, v223, vcc
	v_cndmask_b32_e32 v227, v223, v221, vcc
	v_perm_b32 v228, v225, v224, s10
	v_perm_b32 v229, v225, v224, s11
	v_perm_b32 v230, v227, v226, s10
	v_perm_b32 v231, v227, v226, s11
	s_add_u32 s34, s12, 0x0
	s_addc_u32 s35, s13, 0
	global_store_dword v248, v228, s[34:35]
	global_store_dword v249, v229, s[34:35]
	s_add_u32 s34, s12, 0x10000
	s_addc_u32 s35, s13, 0
	global_store_dword v248, v230, s[34:35]
	global_store_dword v249, v231, s[34:35]
	v_cvt_pk_bf16_f32 v232, v116, v117
	v_cvt_pk_bf16_f32 v233, v118, v119
	v_cvt_pk_bf16_f32 v234, v112, v113
	v_cvt_pk_bf16_f32 v235, v114, v115
	v_cndmask_b32_e64 v236, v232, v233, s[8:9]
	v_cndmask_b32_e64 v237, v234, v235, s[8:9]
	s_nop 0
	v_mov_b32_dpp v236, v236 quad_perm:[1,0,3,2] row_mask:0xf bank_mask:0xf bound_ctrl:1
	v_mov_b32_dpp v237, v237 quad_perm:[1,0,3,2] row_mask:0xf bank_mask:0xf bound_ctrl:1
	v_cndmask_b32_e32 v238, v232, v236, vcc
	v_cndmask_b32_e32 v239, v236, v233, vcc
	v_cndmask_b32_e32 v240, v234, v237, vcc
	v_cndmask_b32_e32 v241, v237, v235, vcc
	v_perm_b32 v242, v239, v238, s10
	v_perm_b32 v243, v239, v238, s11
	v_perm_b32 v244, v241, v240, s10
	v_perm_b32 v245, v241, v240, s11
	s_add_u32 s34, s12, 0x80000
	s_addc_u32 s35, s13, 0
	global_store_dword v248, v242, s[34:35]
	global_store_dword v249, v243, s[34:35]
	s_add_u32 s34, s12, 0x90000
	s_addc_u32 s35, s13, 0
	global_store_dword v248, v244, s[34:35]
	global_store_dword v249, v245, s[34:35]
	v_cvt_pk_bf16_f32 v218, v108, v109
	v_cvt_pk_bf16_f32 v219, v110, v111
	v_cvt_pk_bf16_f32 v220, v104, v105
	v_cvt_pk_bf16_f32 v221, v106, v107
	v_cndmask_b32_e64 v222, v218, v219, s[8:9]
	v_cndmask_b32_e64 v223, v220, v221, s[8:9]
	s_nop 0
	v_mov_b32_dpp v222, v222 quad_perm:[1,0,3,2] row_mask:0xf bank_mask:0xf bound_ctrl:1
	v_mov_b32_dpp v223, v223 quad_perm:[1,0,3,2] row_mask:0xf bank_mask:0xf bound_ctrl:1
	v_cndmask_b32_e32 v224, v218, v222, vcc
	v_cndmask_b32_e32 v225, v222, v219, vcc
	v_cndmask_b32_e32 v226, v220, v223, vcc
	v_cndmask_b32_e32 v227, v223, v221, vcc
	v_perm_b32 v228, v225, v224, s10
	v_perm_b32 v229, v225, v224, s11
	v_perm_b32 v230, v227, v226, s10
	v_perm_b32 v231, v227, v226, s11
	s_add_u32 s34, s12, 0x20
	s_addc_u32 s35, s13, 0
	global_store_dword v248, v228, s[34:35]
	global_store_dword v249, v229, s[34:35]
	s_add_u32 s34, s12, 0x10020
	s_addc_u32 s35, s13, 0
	global_store_dword v248, v230, s[34:35]
	global_store_dword v249, v231, s[34:35]
	v_cvt_pk_bf16_f32 v232, v100, v101
	v_cvt_pk_bf16_f32 v233, v102, v103
	v_cvt_pk_bf16_f32 v234, v96, v97
	v_cvt_pk_bf16_f32 v235, v98, v99
	v_cndmask_b32_e64 v236, v232, v233, s[8:9]
	v_cndmask_b32_e64 v237, v234, v235, s[8:9]
	s_nop 0
	v_mov_b32_dpp v236, v236 quad_perm:[1,0,3,2] row_mask:0xf bank_mask:0xf bound_ctrl:1
	v_mov_b32_dpp v237, v237 quad_perm:[1,0,3,2] row_mask:0xf bank_mask:0xf bound_ctrl:1
	v_cndmask_b32_e32 v238, v232, v236, vcc
	v_cndmask_b32_e32 v239, v236, v233, vcc
	v_cndmask_b32_e32 v240, v234, v237, vcc
	v_cndmask_b32_e32 v241, v237, v235, vcc
	v_perm_b32 v242, v239, v238, s10
	v_perm_b32 v243, v239, v238, s11
	v_perm_b32 v244, v241, v240, s10
	v_perm_b32 v245, v241, v240, s11
	s_add_u32 s34, s12, 0x80020
	s_addc_u32 s35, s13, 0
	global_store_dword v248, v242, s[34:35]
	global_store_dword v249, v243, s[34:35]
	s_add_u32 s34, s12, 0x90020
	s_addc_u32 s35, s13, 0
	global_store_dword v248, v244, s[34:35]
	global_store_dword v249, v245, s[34:35]
	v_cvt_pk_bf16_f32 v218, v92, v93
	v_cvt_pk_bf16_f32 v219, v94, v95
	v_cvt_pk_bf16_f32 v220, v88, v89
	v_cvt_pk_bf16_f32 v221, v90, v91
	v_cndmask_b32_e64 v222, v218, v219, s[8:9]
	v_cndmask_b32_e64 v223, v220, v221, s[8:9]
	s_nop 0
	v_mov_b32_dpp v222, v222 quad_perm:[1,0,3,2] row_mask:0xf bank_mask:0xf bound_ctrl:1
	v_mov_b32_dpp v223, v223 quad_perm:[1,0,3,2] row_mask:0xf bank_mask:0xf bound_ctrl:1
	v_cndmask_b32_e32 v224, v218, v222, vcc
	v_cndmask_b32_e32 v225, v222, v219, vcc
	v_cndmask_b32_e32 v226, v220, v223, vcc
	v_cndmask_b32_e32 v227, v223, v221, vcc
	v_perm_b32 v228, v225, v224, s10
	v_perm_b32 v229, v225, v224, s11
	v_perm_b32 v230, v227, v226, s10
	v_perm_b32 v231, v227, v226, s11
	s_add_u32 s34, s12, 0x40
	s_addc_u32 s35, s13, 0
	global_store_dword v248, v228, s[34:35]
	global_store_dword v249, v229, s[34:35]
	s_add_u32 s34, s12, 0x10040
	s_addc_u32 s35, s13, 0
	global_store_dword v248, v230, s[34:35]
	global_store_dword v249, v231, s[34:35]
	v_cvt_pk_bf16_f32 v232, v84, v85
	v_cvt_pk_bf16_f32 v233, v86, v87
	v_cvt_pk_bf16_f32 v234, v80, v81
	v_cvt_pk_bf16_f32 v235, v82, v83
	v_cndmask_b32_e64 v236, v232, v233, s[8:9]
	v_cndmask_b32_e64 v237, v234, v235, s[8:9]
	s_nop 0
	v_mov_b32_dpp v236, v236 quad_perm:[1,0,3,2] row_mask:0xf bank_mask:0xf bound_ctrl:1
	v_mov_b32_dpp v237, v237 quad_perm:[1,0,3,2] row_mask:0xf bank_mask:0xf bound_ctrl:1
	v_cndmask_b32_e32 v238, v232, v236, vcc
	v_cndmask_b32_e32 v239, v236, v233, vcc
	v_cndmask_b32_e32 v240, v234, v237, vcc
	v_cndmask_b32_e32 v241, v237, v235, vcc
	v_perm_b32 v242, v239, v238, s10
	v_perm_b32 v243, v239, v238, s11
	v_perm_b32 v244, v241, v240, s10
	v_perm_b32 v245, v241, v240, s11
	s_add_u32 s34, s12, 0x80040
	s_addc_u32 s35, s13, 0
	global_store_dword v248, v242, s[34:35]
	global_store_dword v249, v243, s[34:35]
	s_add_u32 s34, s12, 0x90040
	s_addc_u32 s35, s13, 0
	global_store_dword v248, v244, s[34:35]
	global_store_dword v249, v245, s[34:35]
	v_cvt_pk_bf16_f32 v218, v76, v77
	v_cvt_pk_bf16_f32 v219, v78, v79
	v_cvt_pk_bf16_f32 v220, v72, v73
	v_cvt_pk_bf16_f32 v221, v74, v75
	v_cndmask_b32_e64 v222, v218, v219, s[8:9]
	v_cndmask_b32_e64 v223, v220, v221, s[8:9]
	s_nop 0
	v_mov_b32_dpp v222, v222 quad_perm:[1,0,3,2] row_mask:0xf bank_mask:0xf bound_ctrl:1
	v_mov_b32_dpp v223, v223 quad_perm:[1,0,3,2] row_mask:0xf bank_mask:0xf bound_ctrl:1
	v_cndmask_b32_e32 v224, v218, v222, vcc
	v_cndmask_b32_e32 v225, v222, v219, vcc
	v_cndmask_b32_e32 v226, v220, v223, vcc
	v_cndmask_b32_e32 v227, v223, v221, vcc
	v_perm_b32 v228, v225, v224, s10
	v_perm_b32 v229, v225, v224, s11
	v_perm_b32 v230, v227, v226, s10
	v_perm_b32 v231, v227, v226, s11
	s_add_u32 s34, s12, 0x60
	s_addc_u32 s35, s13, 0
	global_store_dword v248, v228, s[34:35]
	global_store_dword v249, v229, s[34:35]
	s_add_u32 s34, s12, 0x10060
	s_addc_u32 s35, s13, 0
	global_store_dword v248, v230, s[34:35]
	global_store_dword v249, v231, s[34:35]
	v_cvt_pk_bf16_f32 v232, v68, v69
	v_cvt_pk_bf16_f32 v233, v70, v71
	v_cvt_pk_bf16_f32 v234, v64, v65
	v_cvt_pk_bf16_f32 v235, v66, v67
	v_cndmask_b32_e64 v236, v232, v233, s[8:9]
	v_cndmask_b32_e64 v237, v234, v235, s[8:9]
	s_nop 0
	v_mov_b32_dpp v236, v236 quad_perm:[1,0,3,2] row_mask:0xf bank_mask:0xf bound_ctrl:1
	v_mov_b32_dpp v237, v237 quad_perm:[1,0,3,2] row_mask:0xf bank_mask:0xf bound_ctrl:1
	v_cndmask_b32_e32 v238, v232, v236, vcc
	v_cndmask_b32_e32 v239, v236, v233, vcc
	v_cndmask_b32_e32 v240, v234, v237, vcc
	v_cndmask_b32_e32 v241, v237, v235, vcc
	v_perm_b32 v242, v239, v238, s10
	v_perm_b32 v243, v239, v238, s11
	v_perm_b32 v244, v241, v240, s10
	v_perm_b32 v245, v241, v240, s11
	s_add_u32 s34, s12, 0x80060
	s_addc_u32 s35, s13, 0
	global_store_dword v248, v242, s[34:35]
	global_store_dword v249, v243, s[34:35]
	s_add_u32 s34, s12, 0x90060
	s_addc_u32 s35, s13, 0
	global_store_dword v248, v244, s[34:35]
	global_store_dword v249, v245, s[34:35]
	v_cvt_pk_bf16_f32 v218, v60, v61
	v_cvt_pk_bf16_f32 v219, v62, v63
	v_cvt_pk_bf16_f32 v220, v56, v57
	v_cvt_pk_bf16_f32 v221, v58, v59
	v_cndmask_b32_e64 v222, v218, v219, s[8:9]
	v_cndmask_b32_e64 v223, v220, v221, s[8:9]
	s_nop 0
	v_mov_b32_dpp v222, v222 quad_perm:[1,0,3,2] row_mask:0xf bank_mask:0xf bound_ctrl:1
	v_mov_b32_dpp v223, v223 quad_perm:[1,0,3,2] row_mask:0xf bank_mask:0xf bound_ctrl:1
	v_cndmask_b32_e32 v224, v218, v222, vcc
	v_cndmask_b32_e32 v225, v222, v219, vcc
	v_cndmask_b32_e32 v226, v220, v223, vcc
	v_cndmask_b32_e32 v227, v223, v221, vcc
	v_perm_b32 v228, v225, v224, s10
	v_perm_b32 v229, v225, v224, s11
	v_perm_b32 v230, v227, v226, s10
	v_perm_b32 v231, v227, v226, s11
	s_add_u32 s34, s12, 0x100
	s_addc_u32 s35, s13, 0
	global_store_dword v248, v228, s[34:35]
	global_store_dword v249, v229, s[34:35]
	s_add_u32 s34, s12, 0x10100
	s_addc_u32 s35, s13, 0
	global_store_dword v248, v230, s[34:35]
	global_store_dword v249, v231, s[34:35]
	v_cvt_pk_bf16_f32 v232, v52, v53
	v_cvt_pk_bf16_f32 v233, v54, v55
	v_cvt_pk_bf16_f32 v234, v48, v49
	v_cvt_pk_bf16_f32 v235, v50, v51
	v_cndmask_b32_e64 v236, v232, v233, s[8:9]
	v_cndmask_b32_e64 v237, v234, v235, s[8:9]
	s_nop 0
	v_mov_b32_dpp v236, v236 quad_perm:[1,0,3,2] row_mask:0xf bank_mask:0xf bound_ctrl:1
	v_mov_b32_dpp v237, v237 quad_perm:[1,0,3,2] row_mask:0xf bank_mask:0xf bound_ctrl:1
	v_cndmask_b32_e32 v238, v232, v236, vcc
	v_cndmask_b32_e32 v239, v236, v233, vcc
	v_cndmask_b32_e32 v240, v234, v237, vcc
	v_cndmask_b32_e32 v241, v237, v235, vcc
	v_perm_b32 v242, v239, v238, s10
	v_perm_b32 v243, v239, v238, s11
	v_perm_b32 v244, v241, v240, s10
	v_perm_b32 v245, v241, v240, s11
	s_add_u32 s34, s12, 0x80100
	s_addc_u32 s35, s13, 0
	global_store_dword v248, v242, s[34:35]
	global_store_dword v249, v243, s[34:35]
	s_add_u32 s34, s12, 0x90100
	s_addc_u32 s35, s13, 0
	global_store_dword v248, v244, s[34:35]
	global_store_dword v249, v245, s[34:35]
	v_cvt_pk_bf16_f32 v218, v44, v45
	v_cvt_pk_bf16_f32 v219, v46, v47
	v_cvt_pk_bf16_f32 v220, v40, v41
	v_cvt_pk_bf16_f32 v221, v42, v43
	v_cndmask_b32_e64 v222, v218, v219, s[8:9]
	v_cndmask_b32_e64 v223, v220, v221, s[8:9]
	s_nop 0
	v_mov_b32_dpp v222, v222 quad_perm:[1,0,3,2] row_mask:0xf bank_mask:0xf bound_ctrl:1
	v_mov_b32_dpp v223, v223 quad_perm:[1,0,3,2] row_mask:0xf bank_mask:0xf bound_ctrl:1
	v_cndmask_b32_e32 v224, v218, v222, vcc
	v_cndmask_b32_e32 v225, v222, v219, vcc
	v_cndmask_b32_e32 v226, v220, v223, vcc
	v_cndmask_b32_e32 v227, v223, v221, vcc
	v_perm_b32 v228, v225, v224, s10
	v_perm_b32 v229, v225, v224, s11
	v_perm_b32 v230, v227, v226, s10
	v_perm_b32 v231, v227, v226, s11
	s_add_u32 s34, s12, 0x120
	s_addc_u32 s35, s13, 0
	global_store_dword v248, v228, s[34:35]
	global_store_dword v249, v229, s[34:35]
	s_add_u32 s34, s12, 0x10120
	s_addc_u32 s35, s13, 0
	global_store_dword v248, v230, s[34:35]
	global_store_dword v249, v231, s[34:35]
	v_cvt_pk_bf16_f32 v232, v36, v37
	v_cvt_pk_bf16_f32 v233, v38, v39
	v_cvt_pk_bf16_f32 v234, v32, v33
	v_cvt_pk_bf16_f32 v235, v34, v35
	v_cndmask_b32_e64 v236, v232, v233, s[8:9]
	v_cndmask_b32_e64 v237, v234, v235, s[8:9]
	s_nop 0
	v_mov_b32_dpp v236, v236 quad_perm:[1,0,3,2] row_mask:0xf bank_mask:0xf bound_ctrl:1
	v_mov_b32_dpp v237, v237 quad_perm:[1,0,3,2] row_mask:0xf bank_mask:0xf bound_ctrl:1
	v_cndmask_b32_e32 v238, v232, v236, vcc
	v_cndmask_b32_e32 v239, v236, v233, vcc
	v_cndmask_b32_e32 v240, v234, v237, vcc
	v_cndmask_b32_e32 v241, v237, v235, vcc
	v_perm_b32 v242, v239, v238, s10
	v_perm_b32 v243, v239, v238, s11
	v_perm_b32 v244, v241, v240, s10
	v_perm_b32 v245, v241, v240, s11
	s_add_u32 s34, s12, 0x80120
	s_addc_u32 s35, s13, 0
	global_store_dword v248, v242, s[34:35]
	global_store_dword v249, v243, s[34:35]
	s_add_u32 s34, s12, 0x90120
	s_addc_u32 s35, s13, 0
	global_store_dword v248, v244, s[34:35]
	global_store_dword v249, v245, s[34:35]
	v_cvt_pk_bf16_f32 v218, v28, v29
	v_cvt_pk_bf16_f32 v219, v30, v31
	v_cvt_pk_bf16_f32 v220, v24, v25
	v_cvt_pk_bf16_f32 v221, v26, v27
	v_cndmask_b32_e64 v222, v218, v219, s[8:9]
	v_cndmask_b32_e64 v223, v220, v221, s[8:9]
	s_nop 0
	v_mov_b32_dpp v222, v222 quad_perm:[1,0,3,2] row_mask:0xf bank_mask:0xf bound_ctrl:1
	v_mov_b32_dpp v223, v223 quad_perm:[1,0,3,2] row_mask:0xf bank_mask:0xf bound_ctrl:1
	v_cndmask_b32_e32 v224, v218, v222, vcc
	v_cndmask_b32_e32 v225, v222, v219, vcc
	v_cndmask_b32_e32 v226, v220, v223, vcc
	v_cndmask_b32_e32 v227, v223, v221, vcc
	v_perm_b32 v228, v225, v224, s10
	v_perm_b32 v229, v225, v224, s11
	v_perm_b32 v230, v227, v226, s10
	v_perm_b32 v231, v227, v226, s11
	s_add_u32 s34, s12, 0x140
	s_addc_u32 s35, s13, 0
	global_store_dword v248, v228, s[34:35]
	global_store_dword v249, v229, s[34:35]
	s_add_u32 s34, s12, 0x10140
	s_addc_u32 s35, s13, 0
	global_store_dword v248, v230, s[34:35]
	global_store_dword v249, v231, s[34:35]
	v_cvt_pk_bf16_f32 v232, v20, v21
	v_cvt_pk_bf16_f32 v233, v22, v23
	v_cvt_pk_bf16_f32 v234, v16, v17
	v_cvt_pk_bf16_f32 v235, v18, v19
	v_cndmask_b32_e64 v236, v232, v233, s[8:9]
	v_cndmask_b32_e64 v237, v234, v235, s[8:9]
	s_nop 0
	v_mov_b32_dpp v236, v236 quad_perm:[1,0,3,2] row_mask:0xf bank_mask:0xf bound_ctrl:1
	v_mov_b32_dpp v237, v237 quad_perm:[1,0,3,2] row_mask:0xf bank_mask:0xf bound_ctrl:1
	v_cndmask_b32_e32 v238, v232, v236, vcc
	v_cndmask_b32_e32 v239, v236, v233, vcc
	v_cndmask_b32_e32 v240, v234, v237, vcc
	v_cndmask_b32_e32 v241, v237, v235, vcc
	v_perm_b32 v242, v239, v238, s10
	v_perm_b32 v243, v239, v238, s11
	v_perm_b32 v244, v241, v240, s10
	v_perm_b32 v245, v241, v240, s11
	s_add_u32 s34, s12, 0x80140
	s_addc_u32 s35, s13, 0
	global_store_dword v248, v242, s[34:35]
	global_store_dword v249, v243, s[34:35]
	s_add_u32 s34, s12, 0x90140
	s_addc_u32 s35, s13, 0
	global_store_dword v248, v244, s[34:35]
	global_store_dword v249, v245, s[34:35]
	v_cvt_pk_bf16_f32 v218, v12, v13
	v_cvt_pk_bf16_f32 v219, v14, v15
	v_cvt_pk_bf16_f32 v220, v8, v9
	v_cvt_pk_bf16_f32 v221, v10, v11
	v_cndmask_b32_e64 v222, v218, v219, s[8:9]
	v_cndmask_b32_e64 v223, v220, v221, s[8:9]
	s_nop 0
	v_mov_b32_dpp v222, v222 quad_perm:[1,0,3,2] row_mask:0xf bank_mask:0xf bound_ctrl:1
	v_mov_b32_dpp v223, v223 quad_perm:[1,0,3,2] row_mask:0xf bank_mask:0xf bound_ctrl:1
	v_cndmask_b32_e32 v224, v218, v222, vcc
	v_cndmask_b32_e32 v225, v222, v219, vcc
	v_cndmask_b32_e32 v226, v220, v223, vcc
	v_cndmask_b32_e32 v227, v223, v221, vcc
	v_perm_b32 v228, v225, v224, s10
	v_perm_b32 v229, v225, v224, s11
	v_perm_b32 v230, v227, v226, s10
	v_perm_b32 v231, v227, v226, s11
	s_add_u32 s34, s12, 0x160
	s_addc_u32 s35, s13, 0
	global_store_dword v248, v228, s[34:35]
	global_store_dword v249, v229, s[34:35]
	s_add_u32 s34, s12, 0x10160
	s_addc_u32 s35, s13, 0
	global_store_dword v248, v230, s[34:35]
	global_store_dword v249, v231, s[34:35]
	v_cvt_pk_bf16_f32 v232, v4, v5
	v_cvt_pk_bf16_f32 v233, v6, v7
	v_cvt_pk_bf16_f32 v234, v0, v1
	v_cvt_pk_bf16_f32 v235, v2, v3
	v_cndmask_b32_e64 v236, v232, v233, s[8:9]
	v_cndmask_b32_e64 v237, v234, v235, s[8:9]
	s_nop 0
	v_mov_b32_dpp v236, v236 quad_perm:[1,0,3,2] row_mask:0xf bank_mask:0xf bound_ctrl:1
	v_mov_b32_dpp v237, v237 quad_perm:[1,0,3,2] row_mask:0xf bank_mask:0xf bound_ctrl:1
	v_cndmask_b32_e32 v238, v232, v236, vcc
	v_cndmask_b32_e32 v239, v236, v233, vcc
	v_cndmask_b32_e32 v240, v234, v237, vcc
	v_cndmask_b32_e32 v241, v237, v235, vcc
	v_perm_b32 v242, v239, v238, s10
	v_perm_b32 v243, v239, v238, s11
	v_perm_b32 v244, v241, v240, s10
	v_perm_b32 v245, v241, v240, s11
	s_add_u32 s34, s12, 0x80160
	s_addc_u32 s35, s13, 0
	global_store_dword v248, v242, s[34:35]
	global_store_dword v249, v243, s[34:35]
	s_add_u32 s34, s12, 0x90160
	s_addc_u32 s35, s13, 0
	global_store_dword v248, v244, s[34:35]
	global_store_dword v249, v245, s[34:35]
	s_branch .Lvf_f_end
.Lvf_f_c:
	v_lshlrev_b32_e32 v129, 2, v186
	v_lshl_add_u32 v129, v128, 1, v129
	v_sub_u32_e32 v130, v217, v128
	v_lshlrev_b32_e32 v130, 1, v130
	v_mul_u32_u24_e32 v129, 0x200, v129
	v_add_u32_e32 v248, v129, v130
	v_add_u32_e32 v249, 0x200, v248
	s_lshr_b32 s58, s17, 8
	s_add_i32 s38, s26, -9
	s_lshl_b32 s38, s38, 22
	s_lshl_b32 s34, s58, 17
	s_add_i32 s38, s38, s34
	s_lshl_b32 s34, s19, 14
	s_add_i32 s38, s38, s34
	s_and_b32 s34, s17, 0xff
	s_lshl_b32 s34, s34, 1
	s_add_i32 s38, s38, s34
	s_add_u32 s12, s30, s38
	s_addc_u32 s13, s31, 0
	s_add_u32 s12, s12, 0xf6a4400
	s_addc_u32 s13, s13, 0
	v_cvt_pk_bf16_f32 v218, v124, v125
	v_cvt_pk_bf16_f32 v219, v126, v127
	v_cvt_pk_bf16_f32 v220, v120, v121
	v_cvt_pk_bf16_f32 v221, v122, v123
	v_cndmask_b32_e64 v222, v218, v219, s[8:9]
	v_cndmask_b32_e64 v223, v220, v221, s[8:9]
	s_nop 0
	v_mov_b32_dpp v222, v222 quad_perm:[1,0,3,2] row_mask:0xf bank_mask:0xf bound_ctrl:1
	v_mov_b32_dpp v223, v223 quad_perm:[1,0,3,2] row_mask:0xf bank_mask:0xf bound_ctrl:1
	v_cndmask_b32_e32 v224, v218, v222, vcc
	v_cndmask_b32_e32 v225, v222, v219, vcc
	v_cndmask_b32_e32 v226, v220, v223, vcc
	v_cndmask_b32_e32 v227, v223, v221, vcc
	v_perm_b32 v228, v225, v224, s10
	v_perm_b32 v229, v225, v224, s11
	v_perm_b32 v230, v227, v226, s10
	v_perm_b32 v231, v227, v226, s11
	s_add_u32 s34, s12, 0x0
	s_addc_u32 s35, s13, 0
	global_store_dword v248, v228, s[34:35]
	global_store_dword v249, v229, s[34:35]
	s_add_u32 s34, s12, 0x2000
	s_addc_u32 s35, s13, 0
	global_store_dword v248, v230, s[34:35]
	global_store_dword v249, v231, s[34:35]
	v_cvt_pk_bf16_f32 v232, v116, v117
	v_cvt_pk_bf16_f32 v233, v118, v119
	v_cvt_pk_bf16_f32 v234, v112, v113
	v_cvt_pk_bf16_f32 v235, v114, v115
	v_cndmask_b32_e64 v236, v232, v233, s[8:9]
	v_cndmask_b32_e64 v237, v234, v235, s[8:9]
	s_nop 0
	v_mov_b32_dpp v236, v236 quad_perm:[1,0,3,2] row_mask:0xf bank_mask:0xf bound_ctrl:1
	v_mov_b32_dpp v237, v237 quad_perm:[1,0,3,2] row_mask:0xf bank_mask:0xf bound_ctrl:1
	v_cndmask_b32_e32 v238, v232, v236, vcc
	v_cndmask_b32_e32 v239, v236, v233, vcc
	v_cndmask_b32_e32 v240, v234, v237, vcc
	v_cndmask_b32_e32 v241, v237, v235, vcc
	v_perm_b32 v242, v239, v238, s10
	v_perm_b32 v243, v239, v238, s11
	v_perm_b32 v244, v241, v240, s10
	v_perm_b32 v245, v241, v240, s11
	s_add_u32 s34, s12, 0x10000
	s_addc_u32 s35, s13, 0
	global_store_dword v248, v242, s[34:35]
	global_store_dword v249, v243, s[34:35]
	s_add_u32 s34, s12, 0x12000
	s_addc_u32 s35, s13, 0
	global_store_dword v248, v244, s[34:35]
	global_store_dword v249, v245, s[34:35]
	v_cvt_pk_bf16_f32 v218, v108, v109
	v_cvt_pk_bf16_f32 v219, v110, v111
	v_cvt_pk_bf16_f32 v220, v104, v105
	v_cvt_pk_bf16_f32 v221, v106, v107
	v_cndmask_b32_e64 v222, v218, v219, s[8:9]
	v_cndmask_b32_e64 v223, v220, v221, s[8:9]
	s_nop 0
	v_mov_b32_dpp v222, v222 quad_perm:[1,0,3,2] row_mask:0xf bank_mask:0xf bound_ctrl:1
	v_mov_b32_dpp v223, v223 quad_perm:[1,0,3,2] row_mask:0xf bank_mask:0xf bound_ctrl:1
	v_cndmask_b32_e32 v224, v218, v222, vcc
	v_cndmask_b32_e32 v225, v222, v219, vcc
	v_cndmask_b32_e32 v226, v220, v223, vcc
	v_cndmask_b32_e32 v227, v223, v221, vcc
	v_perm_b32 v228, v225, v224, s10
	v_perm_b32 v229, v225, v224, s11
	v_perm_b32 v230, v227, v226, s10
	v_perm_b32 v231, v227, v226, s11
	s_add_u32 s34, s12, 0x20
	s_addc_u32 s35, s13, 0
	global_store_dword v248, v228, s[34:35]
	global_store_dword v249, v229, s[34:35]
	s_add_u32 s34, s12, 0x2020
	s_addc_u32 s35, s13, 0
	global_store_dword v248, v230, s[34:35]
	global_store_dword v249, v231, s[34:35]
	v_cvt_pk_bf16_f32 v232, v100, v101
	v_cvt_pk_bf16_f32 v233, v102, v103
	v_cvt_pk_bf16_f32 v234, v96, v97
	v_cvt_pk_bf16_f32 v235, v98, v99
	v_cndmask_b32_e64 v236, v232, v233, s[8:9]
	v_cndmask_b32_e64 v237, v234, v235, s[8:9]
	s_nop 0
	v_mov_b32_dpp v236, v236 quad_perm:[1,0,3,2] row_mask:0xf bank_mask:0xf bound_ctrl:1
	v_mov_b32_dpp v237, v237 quad_perm:[1,0,3,2] row_mask:0xf bank_mask:0xf bound_ctrl:1
	v_cndmask_b32_e32 v238, v232, v236, vcc
	v_cndmask_b32_e32 v239, v236, v233, vcc
	v_cndmask_b32_e32 v240, v234, v237, vcc
	v_cndmask_b32_e32 v241, v237, v235, vcc
	v_perm_b32 v242, v239, v238, s10
	v_perm_b32 v243, v239, v238, s11
	v_perm_b32 v244, v241, v240, s10
	v_perm_b32 v245, v241, v240, s11
	s_add_u32 s34, s12, 0x10020
	s_addc_u32 s35, s13, 0
	global_store_dword v248, v242, s[34:35]
	global_store_dword v249, v243, s[34:35]
	s_add_u32 s34, s12, 0x12020
	s_addc_u32 s35, s13, 0
	global_store_dword v248, v244, s[34:35]
	global_store_dword v249, v245, s[34:35]
	v_cvt_pk_bf16_f32 v218, v92, v93
	v_cvt_pk_bf16_f32 v219, v94, v95
	v_cvt_pk_bf16_f32 v220, v88, v89
	v_cvt_pk_bf16_f32 v221, v90, v91
	v_cndmask_b32_e64 v222, v218, v219, s[8:9]
	v_cndmask_b32_e64 v223, v220, v221, s[8:9]
	s_nop 0
	v_mov_b32_dpp v222, v222 quad_perm:[1,0,3,2] row_mask:0xf bank_mask:0xf bound_ctrl:1
	v_mov_b32_dpp v223, v223 quad_perm:[1,0,3,2] row_mask:0xf bank_mask:0xf bound_ctrl:1
	v_cndmask_b32_e32 v224, v218, v222, vcc
	v_cndmask_b32_e32 v225, v222, v219, vcc
	v_cndmask_b32_e32 v226, v220, v223, vcc
	v_cndmask_b32_e32 v227, v223, v221, vcc
	v_perm_b32 v228, v225, v224, s10
	v_perm_b32 v229, v225, v224, s11
	v_perm_b32 v230, v227, v226, s10
	v_perm_b32 v231, v227, v226, s11
	s_add_u32 s34, s12, 0x40
	s_addc_u32 s35, s13, 0
	global_store_dword v248, v228, s[34:35]
	global_store_dword v249, v229, s[34:35]
	s_add_u32 s34, s12, 0x2040
	s_addc_u32 s35, s13, 0
	global_store_dword v248, v230, s[34:35]
	global_store_dword v249, v231, s[34:35]
	v_cvt_pk_bf16_f32 v232, v84, v85
	v_cvt_pk_bf16_f32 v233, v86, v87
	v_cvt_pk_bf16_f32 v234, v80, v81
	v_cvt_pk_bf16_f32 v235, v82, v83
	v_cndmask_b32_e64 v236, v232, v233, s[8:9]
	v_cndmask_b32_e64 v237, v234, v235, s[8:9]
	s_nop 0
	v_mov_b32_dpp v236, v236 quad_perm:[1,0,3,2] row_mask:0xf bank_mask:0xf bound_ctrl:1
	v_mov_b32_dpp v237, v237 quad_perm:[1,0,3,2] row_mask:0xf bank_mask:0xf bound_ctrl:1
	v_cndmask_b32_e32 v238, v232, v236, vcc
	v_cndmask_b32_e32 v239, v236, v233, vcc
	v_cndmask_b32_e32 v240, v234, v237, vcc
	v_cndmask_b32_e32 v241, v237, v235, vcc
	v_perm_b32 v242, v239, v238, s10
	v_perm_b32 v243, v239, v238, s11
	v_perm_b32 v244, v241, v240, s10
	v_perm_b32 v245, v241, v240, s11
	s_add_u32 s34, s12, 0x10040
	s_addc_u32 s35, s13, 0
	global_store_dword v248, v242, s[34:35]
	global_store_dword v249, v243, s[34:35]
	s_add_u32 s34, s12, 0x12040
	s_addc_u32 s35, s13, 0
	global_store_dword v248, v244, s[34:35]
	global_store_dword v249, v245, s[34:35]
	v_cvt_pk_bf16_f32 v218, v76, v77
	v_cvt_pk_bf16_f32 v219, v78, v79
	v_cvt_pk_bf16_f32 v220, v72, v73
	v_cvt_pk_bf16_f32 v221, v74, v75
	v_cndmask_b32_e64 v222, v218, v219, s[8:9]
	v_cndmask_b32_e64 v223, v220, v221, s[8:9]
	s_nop 0
	v_mov_b32_dpp v222, v222 quad_perm:[1,0,3,2] row_mask:0xf bank_mask:0xf bound_ctrl:1
	v_mov_b32_dpp v223, v223 quad_perm:[1,0,3,2] row_mask:0xf bank_mask:0xf bound_ctrl:1
	v_cndmask_b32_e32 v224, v218, v222, vcc
	v_cndmask_b32_e32 v225, v222, v219, vcc
	v_cndmask_b32_e32 v226, v220, v223, vcc
	v_cndmask_b32_e32 v227, v223, v221, vcc
	v_perm_b32 v228, v225, v224, s10
	v_perm_b32 v229, v225, v224, s11
	v_perm_b32 v230, v227, v226, s10
	v_perm_b32 v231, v227, v226, s11
	s_add_u32 s34, s12, 0x60
	s_addc_u32 s35, s13, 0
	global_store_dword v248, v228, s[34:35]
	global_store_dword v249, v229, s[34:35]
	s_add_u32 s34, s12, 0x2060
	s_addc_u32 s35, s13, 0
	global_store_dword v248, v230, s[34:35]
	global_store_dword v249, v231, s[34:35]
	v_cvt_pk_bf16_f32 v232, v68, v69
	v_cvt_pk_bf16_f32 v233, v70, v71
	v_cvt_pk_bf16_f32 v234, v64, v65
	v_cvt_pk_bf16_f32 v235, v66, v67
	v_cndmask_b32_e64 v236, v232, v233, s[8:9]
	v_cndmask_b32_e64 v237, v234, v235, s[8:9]
	s_nop 0
	v_mov_b32_dpp v236, v236 quad_perm:[1,0,3,2] row_mask:0xf bank_mask:0xf bound_ctrl:1
	v_mov_b32_dpp v237, v237 quad_perm:[1,0,3,2] row_mask:0xf bank_mask:0xf bound_ctrl:1
	v_cndmask_b32_e32 v238, v232, v236, vcc
	v_cndmask_b32_e32 v239, v236, v233, vcc
	v_cndmask_b32_e32 v240, v234, v237, vcc
	v_cndmask_b32_e32 v241, v237, v235, vcc
	v_perm_b32 v242, v239, v238, s10
	v_perm_b32 v243, v239, v238, s11
	v_perm_b32 v244, v241, v240, s10
	v_perm_b32 v245, v241, v240, s11
	s_add_u32 s34, s12, 0x10060
	s_addc_u32 s35, s13, 0
	global_store_dword v248, v242, s[34:35]
	global_store_dword v249, v243, s[34:35]
	s_add_u32 s34, s12, 0x12060
	s_addc_u32 s35, s13, 0
	global_store_dword v248, v244, s[34:35]
	global_store_dword v249, v245, s[34:35]
	v_cvt_pk_bf16_f32 v218, v60, v61
	v_cvt_pk_bf16_f32 v219, v62, v63
	v_cvt_pk_bf16_f32 v220, v56, v57
	v_cvt_pk_bf16_f32 v221, v58, v59
	v_cndmask_b32_e64 v222, v218, v219, s[8:9]
	v_cndmask_b32_e64 v223, v220, v221, s[8:9]
	s_nop 0
	v_mov_b32_dpp v222, v222 quad_perm:[1,0,3,2] row_mask:0xf bank_mask:0xf bound_ctrl:1
	v_mov_b32_dpp v223, v223 quad_perm:[1,0,3,2] row_mask:0xf bank_mask:0xf bound_ctrl:1
	v_cndmask_b32_e32 v224, v218, v222, vcc
	v_cndmask_b32_e32 v225, v222, v219, vcc
	v_cndmask_b32_e32 v226, v220, v223, vcc
	v_cndmask_b32_e32 v227, v223, v221, vcc
	v_perm_b32 v228, v225, v224, s10
	v_perm_b32 v229, v225, v224, s11
	v_perm_b32 v230, v227, v226, s10
	v_perm_b32 v231, v227, v226, s11
	s_add_u32 s34, s12, 0x100
	s_addc_u32 s35, s13, 0
	global_store_dword v248, v228, s[34:35]
	global_store_dword v249, v229, s[34:35]
	s_add_u32 s34, s12, 0x2100
	s_addc_u32 s35, s13, 0
	global_store_dword v248, v230, s[34:35]
	global_store_dword v249, v231, s[34:35]
	v_cvt_pk_bf16_f32 v232, v52, v53
	v_cvt_pk_bf16_f32 v233, v54, v55
	v_cvt_pk_bf16_f32 v234, v48, v49
	v_cvt_pk_bf16_f32 v235, v50, v51
	v_cndmask_b32_e64 v236, v232, v233, s[8:9]
	v_cndmask_b32_e64 v237, v234, v235, s[8:9]
	s_nop 0
	v_mov_b32_dpp v236, v236 quad_perm:[1,0,3,2] row_mask:0xf bank_mask:0xf bound_ctrl:1
	v_mov_b32_dpp v237, v237 quad_perm:[1,0,3,2] row_mask:0xf bank_mask:0xf bound_ctrl:1
	v_cndmask_b32_e32 v238, v232, v236, vcc
	v_cndmask_b32_e32 v239, v236, v233, vcc
	v_cndmask_b32_e32 v240, v234, v237, vcc
	v_cndmask_b32_e32 v241, v237, v235, vcc
	v_perm_b32 v242, v239, v238, s10
	v_perm_b32 v243, v239, v238, s11
	v_perm_b32 v244, v241, v240, s10
	v_perm_b32 v245, v241, v240, s11
	s_add_u32 s34, s12, 0x10100
	s_addc_u32 s35, s13, 0
	global_store_dword v248, v242, s[34:35]
	global_store_dword v249, v243, s[34:35]
	s_add_u32 s34, s12, 0x12100
	s_addc_u32 s35, s13, 0
	global_store_dword v248, v244, s[34:35]
	global_store_dword v249, v245, s[34:35]
	v_cvt_pk_bf16_f32 v218, v44, v45
	v_cvt_pk_bf16_f32 v219, v46, v47
	v_cvt_pk_bf16_f32 v220, v40, v41
	v_cvt_pk_bf16_f32 v221, v42, v43
	v_cndmask_b32_e64 v222, v218, v219, s[8:9]
	v_cndmask_b32_e64 v223, v220, v221, s[8:9]
	s_nop 0
	v_mov_b32_dpp v222, v222 quad_perm:[1,0,3,2] row_mask:0xf bank_mask:0xf bound_ctrl:1
	v_mov_b32_dpp v223, v223 quad_perm:[1,0,3,2] row_mask:0xf bank_mask:0xf bound_ctrl:1
	v_cndmask_b32_e32 v224, v218, v222, vcc
	v_cndmask_b32_e32 v225, v222, v219, vcc
	v_cndmask_b32_e32 v226, v220, v223, vcc
	v_cndmask_b32_e32 v227, v223, v221, vcc
	v_perm_b32 v228, v225, v224, s10
	v_perm_b32 v229, v225, v224, s11
	v_perm_b32 v230, v227, v226, s10
	v_perm_b32 v231, v227, v226, s11
	s_add_u32 s34, s12, 0x120
	s_addc_u32 s35, s13, 0
	global_store_dword v248, v228, s[34:35]
	global_store_dword v249, v229, s[34:35]
	s_add_u32 s34, s12, 0x2120
	s_addc_u32 s35, s13, 0
	global_store_dword v248, v230, s[34:35]
	global_store_dword v249, v231, s[34:35]
	v_cvt_pk_bf16_f32 v232, v36, v37
	v_cvt_pk_bf16_f32 v233, v38, v39
	v_cvt_pk_bf16_f32 v234, v32, v33
	v_cvt_pk_bf16_f32 v235, v34, v35
	v_cndmask_b32_e64 v236, v232, v233, s[8:9]
	v_cndmask_b32_e64 v237, v234, v235, s[8:9]
	s_nop 0
	v_mov_b32_dpp v236, v236 quad_perm:[1,0,3,2] row_mask:0xf bank_mask:0xf bound_ctrl:1
	v_mov_b32_dpp v237, v237 quad_perm:[1,0,3,2] row_mask:0xf bank_mask:0xf bound_ctrl:1
	v_cndmask_b32_e32 v238, v232, v236, vcc
	v_cndmask_b32_e32 v239, v236, v233, vcc
	v_cndmask_b32_e32 v240, v234, v237, vcc
	v_cndmask_b32_e32 v241, v237, v235, vcc
	v_perm_b32 v242, v239, v238, s10
	v_perm_b32 v243, v239, v238, s11
	v_perm_b32 v244, v241, v240, s10
	v_perm_b32 v245, v241, v240, s11
	s_add_u32 s34, s12, 0x10120
	s_addc_u32 s35, s13, 0
	global_store_dword v248, v242, s[34:35]
	global_store_dword v249, v243, s[34:35]
	s_add_u32 s34, s12, 0x12120
	s_addc_u32 s35, s13, 0
	global_store_dword v248, v244, s[34:35]
	global_store_dword v249, v245, s[34:35]
	v_cvt_pk_bf16_f32 v218, v28, v29
	v_cvt_pk_bf16_f32 v219, v30, v31
	v_cvt_pk_bf16_f32 v220, v24, v25
	v_cvt_pk_bf16_f32 v221, v26, v27
	v_cndmask_b32_e64 v222, v218, v219, s[8:9]
	v_cndmask_b32_e64 v223, v220, v221, s[8:9]
	s_nop 0
	v_mov_b32_dpp v222, v222 quad_perm:[1,0,3,2] row_mask:0xf bank_mask:0xf bound_ctrl:1
	v_mov_b32_dpp v223, v223 quad_perm:[1,0,3,2] row_mask:0xf bank_mask:0xf bound_ctrl:1
	v_cndmask_b32_e32 v224, v218, v222, vcc
	v_cndmask_b32_e32 v225, v222, v219, vcc
	v_cndmask_b32_e32 v226, v220, v223, vcc
	v_cndmask_b32_e32 v227, v223, v221, vcc
	v_perm_b32 v228, v225, v224, s10
	v_perm_b32 v229, v225, v224, s11
	v_perm_b32 v230, v227, v226, s10
	v_perm_b32 v231, v227, v226, s11
	s_add_u32 s34, s12, 0x140
	s_addc_u32 s35, s13, 0
	global_store_dword v248, v228, s[34:35]
	global_store_dword v249, v229, s[34:35]
	s_add_u32 s34, s12, 0x2140
	s_addc_u32 s35, s13, 0
	global_store_dword v248, v230, s[34:35]
	global_store_dword v249, v231, s[34:35]
	v_cvt_pk_bf16_f32 v232, v20, v21
	v_cvt_pk_bf16_f32 v233, v22, v23
	v_cvt_pk_bf16_f32 v234, v16, v17
	v_cvt_pk_bf16_f32 v235, v18, v19
	v_cndmask_b32_e64 v236, v232, v233, s[8:9]
	v_cndmask_b32_e64 v237, v234, v235, s[8:9]
	s_nop 0
	v_mov_b32_dpp v236, v236 quad_perm:[1,0,3,2] row_mask:0xf bank_mask:0xf bound_ctrl:1
	v_mov_b32_dpp v237, v237 quad_perm:[1,0,3,2] row_mask:0xf bank_mask:0xf bound_ctrl:1
	v_cndmask_b32_e32 v238, v232, v236, vcc
	v_cndmask_b32_e32 v239, v236, v233, vcc
	v_cndmask_b32_e32 v240, v234, v237, vcc
	v_cndmask_b32_e32 v241, v237, v235, vcc
	v_perm_b32 v242, v239, v238, s10
	v_perm_b32 v243, v239, v238, s11
	v_perm_b32 v244, v241, v240, s10
	v_perm_b32 v245, v241, v240, s11
	s_add_u32 s34, s12, 0x10140
	s_addc_u32 s35, s13, 0
	global_store_dword v248, v242, s[34:35]
	global_store_dword v249, v243, s[34:35]
	s_add_u32 s34, s12, 0x12140
	s_addc_u32 s35, s13, 0
	global_store_dword v248, v244, s[34:35]
	global_store_dword v249, v245, s[34:35]
	v_cvt_pk_bf16_f32 v218, v12, v13
	v_cvt_pk_bf16_f32 v219, v14, v15
	v_cvt_pk_bf16_f32 v220, v8, v9
	v_cvt_pk_bf16_f32 v221, v10, v11
	v_cndmask_b32_e64 v222, v218, v219, s[8:9]
	v_cndmask_b32_e64 v223, v220, v221, s[8:9]
	s_nop 0
	v_mov_b32_dpp v222, v222 quad_perm:[1,0,3,2] row_mask:0xf bank_mask:0xf bound_ctrl:1
	v_mov_b32_dpp v223, v223 quad_perm:[1,0,3,2] row_mask:0xf bank_mask:0xf bound_ctrl:1
	v_cndmask_b32_e32 v224, v218, v222, vcc
	v_cndmask_b32_e32 v225, v222, v219, vcc
	v_cndmask_b32_e32 v226, v220, v223, vcc
	v_cndmask_b32_e32 v227, v223, v221, vcc
	v_perm_b32 v228, v225, v224, s10
	v_perm_b32 v229, v225, v224, s11
	v_perm_b32 v230, v227, v226, s10
	v_perm_b32 v231, v227, v226, s11
	s_add_u32 s34, s12, 0x160
	s_addc_u32 s35, s13, 0
	global_store_dword v248, v228, s[34:35]
	global_store_dword v249, v229, s[34:35]
	s_add_u32 s34, s12, 0x2160
	s_addc_u32 s35, s13, 0
	global_store_dword v248, v230, s[34:35]
	global_store_dword v249, v231, s[34:35]
	v_cvt_pk_bf16_f32 v232, v4, v5
	v_cvt_pk_bf16_f32 v233, v6, v7
	v_cvt_pk_bf16_f32 v234, v0, v1
	v_cvt_pk_bf16_f32 v235, v2, v3
	v_cndmask_b32_e64 v236, v232, v233, s[8:9]
	v_cndmask_b32_e64 v237, v234, v235, s[8:9]
	s_nop 0
	v_mov_b32_dpp v236, v236 quad_perm:[1,0,3,2] row_mask:0xf bank_mask:0xf bound_ctrl:1
	v_mov_b32_dpp v237, v237 quad_perm:[1,0,3,2] row_mask:0xf bank_mask:0xf bound_ctrl:1
	v_cndmask_b32_e32 v238, v232, v236, vcc
	v_cndmask_b32_e32 v239, v236, v233, vcc
	v_cndmask_b32_e32 v240, v234, v237, vcc
	v_cndmask_b32_e32 v241, v237, v235, vcc
	v_perm_b32 v242, v239, v238, s10
	v_perm_b32 v243, v239, v238, s11
	v_perm_b32 v244, v241, v240, s10
	v_perm_b32 v245, v241, v240, s11
	s_add_u32 s34, s12, 0x10160
	s_addc_u32 s35, s13, 0
	global_store_dword v248, v242, s[34:35]
	global_store_dword v249, v243, s[34:35]
	s_add_u32 s34, s12, 0x12160
	s_addc_u32 s35, s13, 0
	global_store_dword v248, v244, s[34:35]
	global_store_dword v249, v245, s[34:35]
	s_branch .Lvf_f_end
.Lvf_f_end:
	s_mov_b64 s[8:9], 0
.LBB0_406:
	s_and_b64 vcc, exec, s[8:9]
	s_cbranch_vccz .LBB0_408
	s_add_i32 s58, s26, -6
	s_lshl_b64 s[8:9], s[58:59], 23
	s_waitcnt lgkmcnt(0)
	s_add_u32 s8, s30, s8
	s_addc_u32 s9, s31, s9
	s_lshl_b32 s10, s19, 6
	s_add_u32 s8, s8, s10
	s_addc_u32 s9, s9, 0
	v_lshlrev_b32_e32 v132, 4, v186
	v_lshl_add_u64 v[128:129], s[8:9], 0, v[132:133]
	s_mov_b64 s[8:9], 0xd6a4400
	v_lshl_add_u64 v[130:131], v[128:129], 0, s[8:9]
	v_ashrrev_i32_e32 v159, 31, v158
	v_lshlrev_b64 v[128:129], 9, v[158:159]
	v_lshl_add_u64 v[128:129], v[130:131], 0, v[128:129]
	v_cvt_pk_bf16_f32 v160, v124, v125
	v_cvt_pk_bf16_f32 v161, v126, v127
	v_cvt_pk_bf16_f32 v162, v120, v121
	v_cvt_pk_bf16_f32 v163, v122, v123
	global_store_dwordx4 v[128:129], v[160:163], off
	s_nop 1
	v_cvt_pk_bf16_f32 v160, v116, v117
	v_cvt_pk_bf16_f32 v161, v118, v119
	v_cvt_pk_bf16_f32 v162, v112, v113
	v_cvt_pk_bf16_f32 v163, v114, v115
	global_store_dwordx4 v[128:129], v[160:163], off offset:256
	s_nop 1
	v_or_b32_e32 v160, 16, v158
	v_ashrrev_i32_e32 v161, 31, v160
	v_lshlrev_b64 v[160:161], 9, v[160:161]
	v_lshl_add_u64 v[164:165], v[130:131], 0, v[160:161]
	v_cvt_pk_bf16_f32 v160, v108, v109
	v_cvt_pk_bf16_f32 v161, v110, v111
	v_cvt_pk_bf16_f32 v162, v104, v105
	v_cvt_pk_bf16_f32 v163, v106, v107
	global_store_dwordx4 v[164:165], v[160:163], off
	s_nop 1
	v_cvt_pk_bf16_f32 v160, v100, v101
	v_cvt_pk_bf16_f32 v161, v102, v103
	v_cvt_pk_bf16_f32 v162, v96, v97
	v_cvt_pk_bf16_f32 v163, v98, v99
	global_store_dwordx4 v[164:165], v[160:163], off offset:256
	s_nop 1
	v_or_b32_e32 v160, 32, v158
	v_ashrrev_i32_e32 v161, 31, v160
	v_lshlrev_b64 v[160:161], 9, v[160:161]
	v_lshl_add_u64 v[164:165], v[130:131], 0, v[160:161]
	v_cvt_pk_bf16_f32 v160, v92, v93
	v_cvt_pk_bf16_f32 v161, v94, v95
	v_cvt_pk_bf16_f32 v162, v88, v89
	v_cvt_pk_bf16_f32 v163, v90, v91
	global_store_dwordx4 v[164:165], v[160:163], off
	s_nop 1
	v_cvt_pk_bf16_f32 v160, v84, v85
	v_cvt_pk_bf16_f32 v161, v86, v87
	v_cvt_pk_bf16_f32 v162, v80, v81
	v_cvt_pk_bf16_f32 v163, v82, v83
	global_store_dwordx4 v[164:165], v[160:163], off offset:256
	s_nop 1
	v_or_b32_e32 v160, 48, v158
	v_ashrrev_i32_e32 v161, 31, v160
	v_lshlrev_b64 v[160:161], 9, v[160:161]
	v_lshl_add_u64 v[130:131], v[130:131], 0, v[160:161]
	v_cvt_pk_bf16_f32 v160, v76, v77
	v_cvt_pk_bf16_f32 v161, v78, v79
	v_cvt_pk_bf16_f32 v162, v72, v73
	v_cvt_pk_bf16_f32 v163, v74, v75
	global_store_dwordx4 v[130:131], v[160:163], off
	s_nop 1
	v_cvt_pk_bf16_f32 v160, v68, v69
	v_cvt_pk_bf16_f32 v161, v70, v71
	v_cvt_pk_bf16_f32 v162, v64, v65
	v_cvt_pk_bf16_f32 v163, v66, v67
	global_store_dwordx4 v[130:131], v[160:163], off offset:256
	v_add_co_u32_e32 v164, vcc, s33, v128
	v_lshl_add_u64 v[130:131], v[128:129], 0, s[74:75]
	v_cvt_pk_bf16_f32 v160, v60, v61
	v_cvt_pk_bf16_f32 v161, v62, v63
	v_cvt_pk_bf16_f32 v162, v56, v57
	v_cvt_pk_bf16_f32 v163, v58, v59
	s_nop 0
	v_addc_co_u32_e32 v165, vcc, 0, v129, vcc
	global_store_dwordx4 v[164:165], v[160:163], off
	s_nop 1
	v_cvt_pk_bf16_f32 v160, v52, v53
	v_cvt_pk_bf16_f32 v161, v54, v55
	v_cvt_pk_bf16_f32 v162, v48, v49
	v_cvt_pk_bf16_f32 v163, v50, v51
	global_store_dwordx4 v[130:131], v[160:163], off offset:256
	s_mov_b64 s[8:9], 0x12000
	v_lshl_add_u64 v[130:131], v[128:129], 0, s[8:9]
	s_mov_b32 s8, 0x12000
	v_add_co_u32_e32 v164, vcc, s8, v128
	v_cvt_pk_bf16_f32 v160, v44, v45
	v_cvt_pk_bf16_f32 v161, v46, v47
	v_cvt_pk_bf16_f32 v162, v40, v41
	v_cvt_pk_bf16_f32 v163, v42, v43
	s_nop 1
	v_addc_co_u32_e32 v165, vcc, 0, v129, vcc
	global_store_dwordx4 v[164:165], v[160:163], off
	s_nop 1
	v_cvt_pk_bf16_f32 v160, v36, v37
	v_cvt_pk_bf16_f32 v161, v38, v39
	v_cvt_pk_bf16_f32 v162, v32, v33
	v_cvt_pk_bf16_f32 v163, v34, v35
	global_store_dwordx4 v[130:131], v[160:163], off offset:256
	s_mov_b64 s[8:9], 0x14000
	v_lshl_add_u64 v[130:131], v[128:129], 0, s[8:9]
	s_mov_b32 s8, 0x14000
	v_add_co_u32_e32 v164, vcc, s8, v128
	v_cvt_pk_bf16_f32 v160, v28, v29
	v_cvt_pk_bf16_f32 v161, v30, v31
	v_cvt_pk_bf16_f32 v162, v24, v25
	v_cvt_pk_bf16_f32 v163, v26, v27
	s_nop 1
	v_addc_co_u32_e32 v165, vcc, 0, v129, vcc
	global_store_dwordx4 v[164:165], v[160:163], off
	s_nop 1
	v_cvt_pk_bf16_f32 v160, v20, v21
	v_cvt_pk_bf16_f32 v161, v22, v23
	v_cvt_pk_bf16_f32 v162, v16, v17
	v_cvt_pk_bf16_f32 v163, v18, v19
	global_store_dwordx4 v[130:131], v[160:163], off offset:256
	s_mov_b64 s[8:9], 0x16000
	v_lshl_add_u64 v[164:165], v[128:129], 0, s[8:9]
	s_mov_b32 s8, 0x16000
	v_add_co_u32_e32 v128, vcc, s8, v128
	v_cvt_pk_bf16_f32 v160, v12, v13
	v_cvt_pk_bf16_f32 v161, v14, v15
	v_cvt_pk_bf16_f32 v162, v8, v9
	v_cvt_pk_bf16_f32 v163, v10, v11
	s_nop 1
	v_addc_co_u32_e32 v129, vcc, 0, v129, vcc
	global_store_dwordx4 v[128:129], v[160:163], off
	v_cvt_pk_bf16_f32 v128, v4, v5
	v_cvt_pk_bf16_f32 v129, v6, v7
	v_cvt_pk_bf16_f32 v130, v0, v1
	v_cvt_pk_bf16_f32 v131, v2, v3
	global_store_dwordx4 v[164:165], v[128:131], off offset:256

.LBB0_409:
	s_andn2_b64 vcc, exec, s[8:9]
	s_cbranch_vccnz .LBB0_828
	s_waitcnt lgkmcnt(0)
	v_and_b32_e32 v128, 1, v166
	v_cmp_eq_u32_e64 s[8:9], 0, v128
	v_cmp_eq_u32_e32 vcc, 1, v128
	s_mov_b32 s10, 0x05040100
	s_mov_b32 s11, 0x07060302
	s_cmp_eq_u32 s6, 0
	s_cbranch_scc1 .Lvf_v_c
.Lvf_v_l:
	v_lshlrev_b32_e32 v129, 2, v186
	v_lshl_add_u32 v129, v128, 1, v129
	v_lshrrev_b32_e32 v130, 2, v217
	v_lshlrev_b32_e32 v130, 3, v130
	v_and_b32_e32 v131, 3, v217
	v_add_u32_e32 v130, v130, v131
	v_sub_u32_e32 v130, v130, v128
	v_lshlrev_b32_e32 v130, 1, v130
	v_mul_u32_u24_e32 v129, 0x1400, v129
	v_add_u32_e32 v248, v129, v130
	v_add_u32_e32 v249, 0x1400, v248
	s_lshr_b32 s58, s17, 8
	s_and_b32 s35, s26, 1
	s_lshl_b32 s35, s35, 1
	s_add_i32 s34, s58, 0xffffffe0
	s_lshr_b32 s34, s34, 3
	s_lshl_b32 s34, s34, 2
	s_add_i32 s34, s34, s35
	s_lshl_b32 s34, s34, 7
	s_lshl_b32 s38, s19, 5
	s_add_i32 s34, s34, s38
	s_mulk_i32 s34, 0xa00
	s_and_b32 s38, s58, 7
	s_lshl_b32 s38, s38, 8
	s_add_i32 s34, s34, s38
	s_and_b32 s38, s17, 0xff
	s_add_i32 s34, s34, s38
	s_lshl_b32 s38, s34, 1
	s_add_u32 s12, s30, s38
	s_addc_u32 s13, s31, 0
	s_add_u32 s12, s12, 0xcca4400
	s_addc_u32 s13, s13, 0
	v_cvt_pk_bf16_f32 v218, v124, v125
	v_cvt_pk_bf16_f32 v219, v126, v127
	v_cvt_pk_bf16_f32 v220, v120, v121
	v_cvt_pk_bf16_f32 v221, v122, v123
	v_cndmask_b32_e64 v222, v218, v219, s[8:9]
	v_cndmask_b32_e64 v223, v220, v221, s[8:9]
	s_nop 0
	v_mov_b32_dpp v222, v222 quad_perm:[1,0,3,2] row_mask:0xf bank_mask:0xf bound_ctrl:1
	v_mov_b32_dpp v223, v223 quad_perm:[1,0,3,2] row_mask:0xf bank_mask:0xf bound_ctrl:1
	v_cndmask_b32_e32 v224, v218, v222, vcc
	v_cndmask_b32_e32 v225, v222, v219, vcc
	v_cndmask_b32_e32 v226, v220, v223, vcc
	v_cndmask_b32_e32 v227, v223, v221, vcc
	v_perm_b32 v228, v225, v224, s10
	v_perm_b32 v229, v225, v224, s11
	v_perm_b32 v230, v227, v226, s10
	v_perm_b32 v231, v227, v226, s11
	s_add_u32 s34, s12, 0x0
	s_addc_u32 s35, s13, 0
	global_store_dword v248, v228, s[34:35]
	global_store_dword v249, v229, s[34:35]
	s_add_u32 s34, s12, 0x14000
	s_addc_u32 s35, s13, 0
	global_store_dword v248, v230, s[34:35]
	global_store_dword v249, v231, s[34:35]
	v_cvt_pk_bf16_f32 v232, v116, v117
	v_cvt_pk_bf16_f32 v233, v118, v119
	v_cvt_pk_bf16_f32 v234, v112, v113
	v_cvt_pk_bf16_f32 v235, v114, v115
	v_cndmask_b32_e64 v236, v232, v233, s[8:9]
	v_cndmask_b32_e64 v237, v234, v235, s[8:9]
	s_nop 0
	v_mov_b32_dpp v236, v236 quad_perm:[1,0,3,2] row_mask:0xf bank_mask:0xf bound_ctrl:1
	v_mov_b32_dpp v237, v237 quad_perm:[1,0,3,2] row_mask:0xf bank_mask:0xf bound_ctrl:1
	v_cndmask_b32_e32 v238, v232, v236, vcc
	v_cndmask_b32_e32 v239, v236, v233, vcc
	v_cndmask_b32_e32 v240, v234, v237, vcc
	v_cndmask_b32_e32 v241, v237, v235, vcc
	v_perm_b32 v242, v239, v238, s10
	v_perm_b32 v243, v239, v238, s11
	v_perm_b32 v244, v241, v240, s10
	v_perm_b32 v245, v241, v240, s11
	s_add_u32 s34, s12, 0xa0000
	s_addc_u32 s35, s13, 0
	global_store_dword v248, v242, s[34:35]
	global_store_dword v249, v243, s[34:35]
	s_add_u32 s34, s12, 0xb4000
	s_addc_u32 s35, s13, 0
	global_store_dword v248, v244, s[34:35]
	global_store_dword v249, v245, s[34:35]
	v_cvt_pk_bf16_f32 v218, v108, v109
	v_cvt_pk_bf16_f32 v219, v110, v111
	v_cvt_pk_bf16_f32 v220, v104, v105
	v_cvt_pk_bf16_f32 v221, v106, v107
	v_cndmask_b32_e64 v222, v218, v219, s[8:9]
	v_cndmask_b32_e64 v223, v220, v221, s[8:9]
	s_nop 0
	v_mov_b32_dpp v222, v222 quad_perm:[1,0,3,2] row_mask:0xf bank_mask:0xf bound_ctrl:1
	v_mov_b32_dpp v223, v223 quad_perm:[1,0,3,2] row_mask:0xf bank_mask:0xf bound_ctrl:1
	v_cndmask_b32_e32 v224, v218, v222, vcc
	v_cndmask_b32_e32 v225, v222, v219, vcc
	v_cndmask_b32_e32 v226, v220, v223, vcc
	v_cndmask_b32_e32 v227, v223, v221, vcc
	v_perm_b32 v228, v225, v224, s10
	v_perm_b32 v229, v225, v224, s11
	v_perm_b32 v230, v227, v226, s10
	v_perm_b32 v231, v227, v226, s11
	s_add_u32 s34, s12, 0x8
	s_addc_u32 s35, s13, 0
	global_store_dword v248, v228, s[34:35]
	global_store_dword v249, v229, s[34:35]
	s_add_u32 s34, s12, 0x14008
	s_addc_u32 s35, s13, 0
	global_store_dword v248, v230, s[34:35]
	global_store_dword v249, v231, s[34:35]
	v_cvt_pk_bf16_f32 v232, v100, v101
	v_cvt_pk_bf16_f32 v233, v102, v103
	v_cvt_pk_bf16_f32 v234, v96, v97
	v_cvt_pk_bf16_f32 v235, v98, v99
	v_cndmask_b32_e64 v236, v232, v233, s[8:9]
	v_cndmask_b32_e64 v237, v234, v235, s[8:9]
	s_nop 0
	v_mov_b32_dpp v236, v236 quad_perm:[1,0,3,2] row_mask:0xf bank_mask:0xf bound_ctrl:1
	v_mov_b32_dpp v237, v237 quad_perm:[1,0,3,2] row_mask:0xf bank_mask:0xf bound_ctrl:1
	v_cndmask_b32_e32 v238, v232, v236, vcc
	v_cndmask_b32_e32 v239, v236, v233, vcc
	v_cndmask_b32_e32 v240, v234, v237, vcc
	v_cndmask_b32_e32 v241, v237, v235, vcc
	v_perm_b32 v242, v239, v238, s10
	v_perm_b32 v243, v239, v238, s11
	v_perm_b32 v244, v241, v240, s10
	v_perm_b32 v245, v241, v240, s11
	s_add_u32 s34, s12, 0xa0008
	s_addc_u32 s35, s13, 0
	global_store_dword v248, v242, s[34:35]
	global_store_dword v249, v243, s[34:35]
	s_add_u32 s34, s12, 0xb4008
	s_addc_u32 s35, s13, 0
	global_store_dword v248, v244, s[34:35]
	global_store_dword v249, v245, s[34:35]
	v_cvt_pk_bf16_f32 v218, v92, v93
	v_cvt_pk_bf16_f32 v219, v94, v95
	v_cvt_pk_bf16_f32 v220, v88, v89
	v_cvt_pk_bf16_f32 v221, v90, v91
	v_cndmask_b32_e64 v222, v218, v219, s[8:9]
	v_cndmask_b32_e64 v223, v220, v221, s[8:9]
	s_nop 0
	v_mov_b32_dpp v222, v222 quad_perm:[1,0,3,2] row_mask:0xf bank_mask:0xf bound_ctrl:1
	v_mov_b32_dpp v223, v223 quad_perm:[1,0,3,2] row_mask:0xf bank_mask:0xf bound_ctrl:1
	v_cndmask_b32_e32 v224, v218, v222, vcc
	v_cndmask_b32_e32 v225, v222, v219, vcc
	v_cndmask_b32_e32 v226, v220, v223, vcc
	v_cndmask_b32_e32 v227, v223, v221, vcc
	v_perm_b32 v228, v225, v224, s10
	v_perm_b32 v229, v225, v224, s11
	v_perm_b32 v230, v227, v226, s10
	v_perm_b32 v231, v227, v226, s11
	s_add_u32 s34, s12, 0x40
	s_addc_u32 s35, s13, 0
	global_store_dword v248, v228, s[34:35]
	global_store_dword v249, v229, s[34:35]
	s_add_u32 s34, s12, 0x14040
	s_addc_u32 s35, s13, 0
	global_store_dword v248, v230, s[34:35]
	global_store_dword v249, v231, s[34:35]
	v_cvt_pk_bf16_f32 v232, v84, v85
	v_cvt_pk_bf16_f32 v233, v86, v87
	v_cvt_pk_bf16_f32 v234, v80, v81
	v_cvt_pk_bf16_f32 v235, v82, v83
	v_cndmask_b32_e64 v236, v232, v233, s[8:9]
	v_cndmask_b32_e64 v237, v234, v235, s[8:9]
	s_nop 0
	v_mov_b32_dpp v236, v236 quad_perm:[1,0,3,2] row_mask:0xf bank_mask:0xf bound_ctrl:1
	v_mov_b32_dpp v237, v237 quad_perm:[1,0,3,2] row_mask:0xf bank_mask:0xf bound_ctrl:1
	v_cndmask_b32_e32 v238, v232, v236, vcc
	v_cndmask_b32_e32 v239, v236, v233, vcc
	v_cndmask_b32_e32 v240, v234, v237, vcc
	v_cndmask_b32_e32 v241, v237, v235, vcc
	v_perm_b32 v242, v239, v238, s10
	v_perm_b32 v243, v239, v238, s11
	v_perm_b32 v244, v241, v240, s10
	v_perm_b32 v245, v241, v240, s11
	s_add_u32 s34, s12, 0xa0040
	s_addc_u32 s35, s13, 0
	global_store_dword v248, v242, s[34:35]
	global_store_dword v249, v243, s[34:35]
	s_add_u32 s34, s12, 0xb4040
	s_addc_u32 s35, s13, 0
	global_store_dword v248, v244, s[34:35]
	global_store_dword v249, v245, s[34:35]
	v_cvt_pk_bf16_f32 v218, v76, v77
	v_cvt_pk_bf16_f32 v219, v78, v79
	v_cvt_pk_bf16_f32 v220, v72, v73
	v_cvt_pk_bf16_f32 v221, v74, v75
	v_cndmask_b32_e64 v222, v218, v219, s[8:9]
	v_cndmask_b32_e64 v223, v220, v221, s[8:9]
	s_nop 0
	v_mov_b32_dpp v222, v222 quad_perm:[1,0,3,2] row_mask:0xf bank_mask:0xf bound_ctrl:1
	v_mov_b32_dpp v223, v223 quad_perm:[1,0,3,2] row_mask:0xf bank_mask:0xf bound_ctrl:1
	v_cndmask_b32_e32 v224, v218, v222, vcc
	v_cndmask_b32_e32 v225, v222, v219, vcc
	v_cndmask_b32_e32 v226, v220, v223, vcc
	v_cndmask_b32_e32 v227, v223, v221, vcc
	v_perm_b32 v228, v225, v224, s10
	v_perm_b32 v229, v225, v224, s11
	v_perm_b32 v230, v227, v226, s10
	v_perm_b32 v231, v227, v226, s11
	s_add_u32 s34, s12, 0x48
	s_addc_u32 s35, s13, 0
	global_store_dword v248, v228, s[34:35]
	global_store_dword v249, v229, s[34:35]
	s_add_u32 s34, s12, 0x14048
	s_addc_u32 s35, s13, 0
	global_store_dword v248, v230, s[34:35]
	global_store_dword v249, v231, s[34:35]
	v_cvt_pk_bf16_f32 v232, v68, v69
	v_cvt_pk_bf16_f32 v233, v70, v71
	v_cvt_pk_bf16_f32 v234, v64, v65
	v_cvt_pk_bf16_f32 v235, v66, v67
	v_cndmask_b32_e64 v236, v232, v233, s[8:9]
	v_cndmask_b32_e64 v237, v234, v235, s[8:9]
	s_nop 0
	v_mov_b32_dpp v236, v236 quad_perm:[1,0,3,2] row_mask:0xf bank_mask:0xf bound_ctrl:1
	v_mov_b32_dpp v237, v237 quad_perm:[1,0,3,2] row_mask:0xf bank_mask:0xf bound_ctrl:1
	v_cndmask_b32_e32 v238, v232, v236, vcc
	v_cndmask_b32_e32 v239, v236, v233, vcc
	v_cndmask_b32_e32 v240, v234, v237, vcc
	v_cndmask_b32_e32 v241, v237, v235, vcc
	v_perm_b32 v242, v239, v238, s10
	v_perm_b32 v243, v239, v238, s11
	v_perm_b32 v244, v241, v240, s10
	v_perm_b32 v245, v241, v240, s11
	s_add_u32 s34, s12, 0xa0048
	s_addc_u32 s35, s13, 0
	global_store_dword v248, v242, s[34:35]
	global_store_dword v249, v243, s[34:35]
	s_add_u32 s34, s12, 0xb4048
	s_addc_u32 s35, s13, 0
	global_store_dword v248, v244, s[34:35]
	global_store_dword v249, v245, s[34:35]
	v_cvt_pk_bf16_f32 v218, v60, v61
	v_cvt_pk_bf16_f32 v219, v62, v63
	v_cvt_pk_bf16_f32 v220, v56, v57
	v_cvt_pk_bf16_f32 v221, v58, v59
	v_cndmask_b32_e64 v222, v218, v219, s[8:9]
	v_cndmask_b32_e64 v223, v220, v221, s[8:9]
	s_nop 0
	v_mov_b32_dpp v222, v222 quad_perm:[1,0,3,2] row_mask:0xf bank_mask:0xf bound_ctrl:1
	v_mov_b32_dpp v223, v223 quad_perm:[1,0,3,2] row_mask:0xf bank_mask:0xf bound_ctrl:1
	v_cndmask_b32_e32 v224, v218, v222, vcc
	v_cndmask_b32_e32 v225, v222, v219, vcc
	v_cndmask_b32_e32 v226, v220, v223, vcc
	v_cndmask_b32_e32 v227, v223, v221, vcc
	v_perm_b32 v228, v225, v224, s10
	v_perm_b32 v229, v225, v224, s11
	v_perm_b32 v230, v227, v226, s10
	v_perm_b32 v231, v227, v226, s11
	s_add_u32 s34, s12, 0x100
	s_addc_u32 s35, s13, 0
	global_store_dword v248, v228, s[34:35]
	global_store_dword v249, v229, s[34:35]
	s_add_u32 s34, s12, 0x14100
	s_addc_u32 s35, s13, 0
	global_store_dword v248, v230, s[34:35]
	global_store_dword v249, v231, s[34:35]
	v_cvt_pk_bf16_f32 v232, v52, v53
	v_cvt_pk_bf16_f32 v233, v54, v55
	v_cvt_pk_bf16_f32 v234, v48, v49
	v_cvt_pk_bf16_f32 v235, v50, v51
	v_cndmask_b32_e64 v236, v232, v233, s[8:9]
	v_cndmask_b32_e64 v237, v234, v235, s[8:9]
	s_nop 0
	v_mov_b32_dpp v236, v236 quad_perm:[1,0,3,2] row_mask:0xf bank_mask:0xf bound_ctrl:1
	v_mov_b32_dpp v237, v237 quad_perm:[1,0,3,2] row_mask:0xf bank_mask:0xf bound_ctrl:1
	v_cndmask_b32_e32 v238, v232, v236, vcc
	v_cndmask_b32_e32 v239, v236, v233, vcc
	v_cndmask_b32_e32 v240, v234, v237, vcc
	v_cndmask_b32_e32 v241, v237, v235, vcc
	v_perm_b32 v242, v239, v238, s10
	v_perm_b32 v243, v239, v238, s11
	v_perm_b32 v244, v241, v240, s10
	v_perm_b32 v245, v241, v240, s11
	s_add_u32 s34, s12, 0xa0100
	s_addc_u32 s35, s13, 0
	global_store_dword v248, v242, s[34:35]
	global_store_dword v249, v243, s[34:35]
	s_add_u32 s34, s12, 0xb4100
	s_addc_u32 s35, s13, 0
	global_store_dword v248, v244, s[34:35]
	global_store_dword v249, v245, s[34:35]
	v_cvt_pk_bf16_f32 v218, v44, v45
	v_cvt_pk_bf16_f32 v219, v46, v47
	v_cvt_pk_bf16_f32 v220, v40, v41
	v_cvt_pk_bf16_f32 v221, v42, v43
	v_cndmask_b32_e64 v222, v218, v219, s[8:9]
	v_cndmask_b32_e64 v223, v220, v221, s[8:9]
	s_nop 0
	v_mov_b32_dpp v222, v222 quad_perm:[1,0,3,2] row_mask:0xf bank_mask:0xf bound_ctrl:1
	v_mov_b32_dpp v223, v223 quad_perm:[1,0,3,2] row_mask:0xf bank_mask:0xf bound_ctrl:1
	v_cndmask_b32_e32 v224, v218, v222, vcc
	v_cndmask_b32_e32 v225, v222, v219, vcc
	v_cndmask_b32_e32 v226, v220, v223, vcc
	v_cndmask_b32_e32 v227, v223, v221, vcc
	v_perm_b32 v228, v225, v224, s10
	v_perm_b32 v229, v225, v224, s11
	v_perm_b32 v230, v227, v226, s10
	v_perm_b32 v231, v227, v226, s11
	s_add_u32 s34, s12, 0x108
	s_addc_u32 s35, s13, 0
	global_store_dword v248, v228, s[34:35]
	global_store_dword v249, v229, s[34:35]
	s_add_u32 s34, s12, 0x14108
	s_addc_u32 s35, s13, 0
	global_store_dword v248, v230, s[34:35]
	global_store_dword v249, v231, s[34:35]
	v_cvt_pk_bf16_f32 v232, v36, v37
	v_cvt_pk_bf16_f32 v233, v38, v39
	v_cvt_pk_bf16_f32 v234, v32, v33
	v_cvt_pk_bf16_f32 v235, v34, v35
	v_cndmask_b32_e64 v236, v232, v233, s[8:9]
	v_cndmask_b32_e64 v237, v234, v235, s[8:9]
	s_nop 0
	v_mov_b32_dpp v236, v236 quad_perm:[1,0,3,2] row_mask:0xf bank_mask:0xf bound_ctrl:1
	v_mov_b32_dpp v237, v237 quad_perm:[1,0,3,2] row_mask:0xf bank_mask:0xf bound_ctrl:1
	v_cndmask_b32_e32 v238, v232, v236, vcc
	v_cndmask_b32_e32 v239, v236, v233, vcc
	v_cndmask_b32_e32 v240, v234, v237, vcc
	v_cndmask_b32_e32 v241, v237, v235, vcc
	v_perm_b32 v242, v239, v238, s10
	v_perm_b32 v243, v239, v238, s11
	v_perm_b32 v244, v241, v240, s10
	v_perm_b32 v245, v241, v240, s11
	s_add_u32 s34, s12, 0xa0108
	s_addc_u32 s35, s13, 0
	global_store_dword v248, v242, s[34:35]
	global_store_dword v249, v243, s[34:35]
	s_add_u32 s34, s12, 0xb4108
	s_addc_u32 s35, s13, 0
	global_store_dword v248, v244, s[34:35]
	global_store_dword v249, v245, s[34:35]
	v_cvt_pk_bf16_f32 v218, v28, v29
	v_cvt_pk_bf16_f32 v219, v30, v31
	v_cvt_pk_bf16_f32 v220, v24, v25
	v_cvt_pk_bf16_f32 v221, v26, v27
	v_cndmask_b32_e64 v222, v218, v219, s[8:9]
	v_cndmask_b32_e64 v223, v220, v221, s[8:9]
	s_nop 0
	v_mov_b32_dpp v222, v222 quad_perm:[1,0,3,2] row_mask:0xf bank_mask:0xf bound_ctrl:1
	v_mov_b32_dpp v223, v223 quad_perm:[1,0,3,2] row_mask:0xf bank_mask:0xf bound_ctrl:1
	v_cndmask_b32_e32 v224, v218, v222, vcc
	v_cndmask_b32_e32 v225, v222, v219, vcc
	v_cndmask_b32_e32 v226, v220, v223, vcc
	v_cndmask_b32_e32 v227, v223, v221, vcc
	v_perm_b32 v228, v225, v224, s10
	v_perm_b32 v229, v225, v224, s11
	v_perm_b32 v230, v227, v226, s10
	v_perm_b32 v231, v227, v226, s11
	s_add_u32 s34, s12, 0x140
	s_addc_u32 s35, s13, 0
	global_store_dword v248, v228, s[34:35]
	global_store_dword v249, v229, s[34:35]
	s_add_u32 s34, s12, 0x14140
	s_addc_u32 s35, s13, 0
	global_store_dword v248, v230, s[34:35]
	global_store_dword v249, v231, s[34:35]
	v_cvt_pk_bf16_f32 v232, v20, v21
	v_cvt_pk_bf16_f32 v233, v22, v23
	v_cvt_pk_bf16_f32 v234, v16, v17
	v_cvt_pk_bf16_f32 v235, v18, v19
	v_cndmask_b32_e64 v236, v232, v233, s[8:9]
	v_cndmask_b32_e64 v237, v234, v235, s[8:9]
	s_nop 0
	v_mov_b32_dpp v236, v236 quad_perm:[1,0,3,2] row_mask:0xf bank_mask:0xf bound_ctrl:1
	v_mov_b32_dpp v237, v237 quad_perm:[1,0,3,2] row_mask:0xf bank_mask:0xf bound_ctrl:1
	v_cndmask_b32_e32 v238, v232, v236, vcc
	v_cndmask_b32_e32 v239, v236, v233, vcc
	v_cndmask_b32_e32 v240, v234, v237, vcc
	v_cndmask_b32_e32 v241, v237, v235, vcc
	v_perm_b32 v242, v239, v238, s10
	v_perm_b32 v243, v239, v238, s11
	v_perm_b32 v244, v241, v240, s10
	v_perm_b32 v245, v241, v240, s11
	s_add_u32 s34, s12, 0xa0140
	s_addc_u32 s35, s13, 0
	global_store_dword v248, v242, s[34:35]
	global_store_dword v249, v243, s[34:35]
	s_add_u32 s34, s12, 0xb4140
	s_addc_u32 s35, s13, 0
	global_store_dword v248, v244, s[34:35]
	global_store_dword v249, v245, s[34:35]
	v_cvt_pk_bf16_f32 v218, v12, v13
	v_cvt_pk_bf16_f32 v219, v14, v15
	v_cvt_pk_bf16_f32 v220, v8, v9
	v_cvt_pk_bf16_f32 v221, v10, v11
	v_cndmask_b32_e64 v222, v218, v219, s[8:9]
	v_cndmask_b32_e64 v223, v220, v221, s[8:9]
	s_nop 0
	v_mov_b32_dpp v222, v222 quad_perm:[1,0,3,2] row_mask:0xf bank_mask:0xf bound_ctrl:1
	v_mov_b32_dpp v223, v223 quad_perm:[1,0,3,2] row_mask:0xf bank_mask:0xf bound_ctrl:1
	v_cndmask_b32_e32 v224, v218, v222, vcc
	v_cndmask_b32_e32 v225, v222, v219, vcc
	v_cndmask_b32_e32 v226, v220, v223, vcc
	v_cndmask_b32_e32 v227, v223, v221, vcc
	v_perm_b32 v228, v225, v224, s10
	v_perm_b32 v229, v225, v224, s11
	v_perm_b32 v230, v227, v226, s10
	v_perm_b32 v231, v227, v226, s11
	s_add_u32 s34, s12, 0x148
	s_addc_u32 s35, s13, 0
	global_store_dword v248, v228, s[34:35]
	global_store_dword v249, v229, s[34:35]
	s_add_u32 s34, s12, 0x14148
	s_addc_u32 s35, s13, 0
	global_store_dword v248, v230, s[34:35]
	global_store_dword v249, v231, s[34:35]
	v_cvt_pk_bf16_f32 v232, v4, v5
	v_cvt_pk_bf16_f32 v233, v6, v7
	v_cvt_pk_bf16_f32 v234, v0, v1
	v_cvt_pk_bf16_f32 v235, v2, v3
	v_cndmask_b32_e64 v236, v232, v233, s[8:9]
	v_cndmask_b32_e64 v237, v234, v235, s[8:9]
	s_nop 0
	v_mov_b32_dpp v236, v236 quad_perm:[1,0,3,2] row_mask:0xf bank_mask:0xf bound_ctrl:1
	v_mov_b32_dpp v237, v237 quad_perm:[1,0,3,2] row_mask:0xf bank_mask:0xf bound_ctrl:1
	v_cndmask_b32_e32 v238, v232, v236, vcc
	v_cndmask_b32_e32 v239, v236, v233, vcc
	v_cndmask_b32_e32 v240, v234, v237, vcc
	v_cndmask_b32_e32 v241, v237, v235, vcc
	v_perm_b32 v242, v239, v238, s10
	v_perm_b32 v243, v239, v238, s11
	v_perm_b32 v244, v241, v240, s10
	v_perm_b32 v245, v241, v240, s11
	s_add_u32 s34, s12, 0xa0148
	s_addc_u32 s35, s13, 0
	global_store_dword v248, v242, s[34:35]
	global_store_dword v249, v243, s[34:35]
	s_add_u32 s34, s12, 0xb4148
	s_addc_u32 s35, s13, 0
	global_store_dword v248, v244, s[34:35]
	global_store_dword v249, v245, s[34:35]
	s_branch .Lvf_v_end
.Lvf_v_c:
	v_lshlrev_b32_e32 v129, 2, v186
	v_lshl_add_u32 v129, v128, 1, v129
	v_lshrrev_b32_e32 v130, 2, v217
	v_lshlrev_b32_e32 v130, 3, v130
	v_and_b32_e32 v131, 3, v217
	v_add_u32_e32 v130, v130, v131
	v_sub_u32_e32 v130, v130, v128
	v_lshlrev_b32_e32 v130, 1, v130
	v_mul_u32_u24_e32 v129, 0x200, v129
	v_add_u32_e32 v248, v129, v130
	v_add_u32_e32 v249, 0x200, v248
	s_lshr_b32 s58, s17, 8
	s_and_b32 s35, s26, 1
	s_lshl_b32 s35, s35, 1
	s_lshl_b32 s34, s58, 2
	s_add_i32 s34, s34, s35
	s_lshl_b32 s34, s34, 7
	s_lshl_b32 s38, s19, 5
	s_add_i32 s34, s34, s38
	s_lshl_b32 s34, s34, 8
	s_and_b32 s38, s17, 0xff
	s_add_i32 s34, s34, s38
	s_lshl_b32 s38, s34, 1
	s_add_u32 s12, s30, s38
	s_addc_u32 s13, s31, 0
	s_add_u32 s12, s12, 0xbaa4400
	s_addc_u32 s13, s13, 0
	v_lshlrev_b32_e32 v129, 4, v186
	v_lshl_add_u32 v250, v217, 11, v129
	s_lshl_b32 s34, s58, 1
	s_add_i32 s34, s34, s40
	s_lshl_b32 s34, s34, 8
	s_and_b32 s38, s17, 0xff
	s_add_i32 s34, s34, s38
	s_lshl_b32 s34, s34, 11
	s_lshl_b32 s38, s35, 7
	s_lshl_b32 s58, s19, 5
	s_add_i32 s38, s38, s58
	s_lshl_b32 s38, s38, 2
	s_add_i32 s34, s34, s38
	s_add_u32 s2, s28, s34
	s_addc_u32 s3, s29, 0
	s_add_u32 s2, s2, 0x6000000
	s_addc_u32 s3, s3, 0
	s_add_u32 s6, s2, 0x0
	s_addc_u32 s7, s3, 0
	global_store_dwordx4 v250, v[124:127], s[6:7] offset:0
	global_store_dwordx4 v250, v[120:123], s[6:7] offset:64
	v_cvt_pk_bf16_f32 v218, v124, v125
	v_cvt_pk_bf16_f32 v219, v126, v127
	v_cvt_pk_bf16_f32 v220, v120, v121
	v_cvt_pk_bf16_f32 v221, v122, v123
	v_cndmask_b32_e64 v222, v218, v219, s[8:9]
	v_cndmask_b32_e64 v223, v220, v221, s[8:9]
	s_nop 0
	v_mov_b32_dpp v222, v222 quad_perm:[1,0,3,2] row_mask:0xf bank_mask:0xf bound_ctrl:1
	v_mov_b32_dpp v223, v223 quad_perm:[1,0,3,2] row_mask:0xf bank_mask:0xf bound_ctrl:1
	v_cndmask_b32_e32 v224, v218, v222, vcc
	v_cndmask_b32_e32 v225, v222, v219, vcc
	v_cndmask_b32_e32 v226, v220, v223, vcc
	v_cndmask_b32_e32 v227, v223, v221, vcc
	v_perm_b32 v228, v225, v224, s10
	v_perm_b32 v229, v225, v224, s11
	v_perm_b32 v230, v227, v226, s10
	v_perm_b32 v231, v227, v226, s11
	s_add_u32 s34, s12, 0x0
	s_addc_u32 s35, s13, 0
	global_store_dword v248, v228, s[34:35]
	global_store_dword v249, v229, s[34:35]
	s_add_u32 s34, s12, 0x2000
	s_addc_u32 s35, s13, 0
	global_store_dword v248, v230, s[34:35]
	global_store_dword v249, v231, s[34:35]
	global_store_dwordx4 v250, v[116:119], s[6:7] offset:512
	global_store_dwordx4 v250, v[112:115], s[6:7] offset:576
	v_cvt_pk_bf16_f32 v232, v116, v117
	v_cvt_pk_bf16_f32 v233, v118, v119
	v_cvt_pk_bf16_f32 v234, v112, v113
	v_cvt_pk_bf16_f32 v235, v114, v115
	v_cndmask_b32_e64 v236, v232, v233, s[8:9]
	v_cndmask_b32_e64 v237, v234, v235, s[8:9]
	s_nop 0
	v_mov_b32_dpp v236, v236 quad_perm:[1,0,3,2] row_mask:0xf bank_mask:0xf bound_ctrl:1
	v_mov_b32_dpp v237, v237 quad_perm:[1,0,3,2] row_mask:0xf bank_mask:0xf bound_ctrl:1
	v_cndmask_b32_e32 v238, v232, v236, vcc
	v_cndmask_b32_e32 v239, v236, v233, vcc
	v_cndmask_b32_e32 v240, v234, v237, vcc
	v_cndmask_b32_e32 v241, v237, v235, vcc
	v_perm_b32 v242, v239, v238, s10
	v_perm_b32 v243, v239, v238, s11
	v_perm_b32 v244, v241, v240, s10
	v_perm_b32 v245, v241, v240, s11
	s_add_u32 s34, s12, 0x10000
	s_addc_u32 s35, s13, 0
	global_store_dword v248, v242, s[34:35]
	global_store_dword v249, v243, s[34:35]
	s_add_u32 s34, s12, 0x12000
	s_addc_u32 s35, s13, 0
	global_store_dword v248, v244, s[34:35]
	global_store_dword v249, v245, s[34:35]
	s_add_u32 s6, s2, 0x8000
	s_addc_u32 s7, s3, 0
	global_store_dwordx4 v250, v[108:111], s[6:7] offset:0
	global_store_dwordx4 v250, v[104:107], s[6:7] offset:64
	v_cvt_pk_bf16_f32 v218, v108, v109
	v_cvt_pk_bf16_f32 v219, v110, v111
	v_cvt_pk_bf16_f32 v220, v104, v105
	v_cvt_pk_bf16_f32 v221, v106, v107
	v_cndmask_b32_e64 v222, v218, v219, s[8:9]
	v_cndmask_b32_e64 v223, v220, v221, s[8:9]
	s_nop 0
	v_mov_b32_dpp v222, v222 quad_perm:[1,0,3,2] row_mask:0xf bank_mask:0xf bound_ctrl:1
	v_mov_b32_dpp v223, v223 quad_perm:[1,0,3,2] row_mask:0xf bank_mask:0xf bound_ctrl:1
	v_cndmask_b32_e32 v224, v218, v222, vcc
	v_cndmask_b32_e32 v225, v222, v219, vcc
	v_cndmask_b32_e32 v226, v220, v223, vcc
	v_cndmask_b32_e32 v227, v223, v221, vcc
	v_perm_b32 v228, v225, v224, s10
	v_perm_b32 v229, v225, v224, s11
	v_perm_b32 v230, v227, v226, s10
	v_perm_b32 v231, v227, v226, s11
	s_add_u32 s34, s12, 0x8
	s_addc_u32 s35, s13, 0
	global_store_dword v248, v228, s[34:35]
	global_store_dword v249, v229, s[34:35]
	s_add_u32 s34, s12, 0x2008
	s_addc_u32 s35, s13, 0
	global_store_dword v248, v230, s[34:35]
	global_store_dword v249, v231, s[34:35]
	global_store_dwordx4 v250, v[100:103], s[6:7] offset:512
	global_store_dwordx4 v250, v[96:99], s[6:7] offset:576
	v_cvt_pk_bf16_f32 v232, v100, v101
	v_cvt_pk_bf16_f32 v233, v102, v103
	v_cvt_pk_bf16_f32 v234, v96, v97
	v_cvt_pk_bf16_f32 v235, v98, v99
	v_cndmask_b32_e64 v236, v232, v233, s[8:9]
	v_cndmask_b32_e64 v237, v234, v235, s[8:9]
	s_nop 0
	v_mov_b32_dpp v236, v236 quad_perm:[1,0,3,2] row_mask:0xf bank_mask:0xf bound_ctrl:1
	v_mov_b32_dpp v237, v237 quad_perm:[1,0,3,2] row_mask:0xf bank_mask:0xf bound_ctrl:1
	v_cndmask_b32_e32 v238, v232, v236, vcc
	v_cndmask_b32_e32 v239, v236, v233, vcc
	v_cndmask_b32_e32 v240, v234, v237, vcc
	v_cndmask_b32_e32 v241, v237, v235, vcc
	v_perm_b32 v242, v239, v238, s10
	v_perm_b32 v243, v239, v238, s11
	v_perm_b32 v244, v241, v240, s10
	v_perm_b32 v245, v241, v240, s11
	s_add_u32 s34, s12, 0x10008
	s_addc_u32 s35, s13, 0
	global_store_dword v248, v242, s[34:35]
	global_store_dword v249, v243, s[34:35]
	s_add_u32 s34, s12, 0x12008
	s_addc_u32 s35, s13, 0
	global_store_dword v248, v244, s[34:35]
	global_store_dword v249, v245, s[34:35]
	s_add_u32 s6, s2, 0x10000
	s_addc_u32 s7, s3, 0
	global_store_dwordx4 v250, v[92:95], s[6:7] offset:0
	global_store_dwordx4 v250, v[88:91], s[6:7] offset:64
	v_cvt_pk_bf16_f32 v218, v92, v93
	v_cvt_pk_bf16_f32 v219, v94, v95
	v_cvt_pk_bf16_f32 v220, v88, v89
	v_cvt_pk_bf16_f32 v221, v90, v91
	v_cndmask_b32_e64 v222, v218, v219, s[8:9]
	v_cndmask_b32_e64 v223, v220, v221, s[8:9]
	s_nop 0
	v_mov_b32_dpp v222, v222 quad_perm:[1,0,3,2] row_mask:0xf bank_mask:0xf bound_ctrl:1
	v_mov_b32_dpp v223, v223 quad_perm:[1,0,3,2] row_mask:0xf bank_mask:0xf bound_ctrl:1
	v_cndmask_b32_e32 v224, v218, v222, vcc
	v_cndmask_b32_e32 v225, v222, v219, vcc
	v_cndmask_b32_e32 v226, v220, v223, vcc
	v_cndmask_b32_e32 v227, v223, v221, vcc
	v_perm_b32 v228, v225, v224, s10
	v_perm_b32 v229, v225, v224, s11
	v_perm_b32 v230, v227, v226, s10
	v_perm_b32 v231, v227, v226, s11
	s_add_u32 s34, s12, 0x40
	s_addc_u32 s35, s13, 0
	global_store_dword v248, v228, s[34:35]
	global_store_dword v249, v229, s[34:35]
	s_add_u32 s34, s12, 0x2040
	s_addc_u32 s35, s13, 0
	global_store_dword v248, v230, s[34:35]
	global_store_dword v249, v231, s[34:35]
	global_store_dwordx4 v250, v[84:87], s[6:7] offset:512
	global_store_dwordx4 v250, v[80:83], s[6:7] offset:576
	v_cvt_pk_bf16_f32 v232, v84, v85
	v_cvt_pk_bf16_f32 v233, v86, v87
	v_cvt_pk_bf16_f32 v234, v80, v81
	v_cvt_pk_bf16_f32 v235, v82, v83
	v_cndmask_b32_e64 v236, v232, v233, s[8:9]
	v_cndmask_b32_e64 v237, v234, v235, s[8:9]
	s_nop 0
	v_mov_b32_dpp v236, v236 quad_perm:[1,0,3,2] row_mask:0xf bank_mask:0xf bound_ctrl:1
	v_mov_b32_dpp v237, v237 quad_perm:[1,0,3,2] row_mask:0xf bank_mask:0xf bound_ctrl:1
	v_cndmask_b32_e32 v238, v232, v236, vcc
	v_cndmask_b32_e32 v239, v236, v233, vcc
	v_cndmask_b32_e32 v240, v234, v237, vcc
	v_cndmask_b32_e32 v241, v237, v235, vcc
	v_perm_b32 v242, v239, v238, s10
	v_perm_b32 v243, v239, v238, s11
	v_perm_b32 v244, v241, v240, s10
	v_perm_b32 v245, v241, v240, s11
	s_add_u32 s34, s12, 0x10040
	s_addc_u32 s35, s13, 0
	global_store_dword v248, v242, s[34:35]
	global_store_dword v249, v243, s[34:35]
	s_add_u32 s34, s12, 0x12040
	s_addc_u32 s35, s13, 0
	global_store_dword v248, v244, s[34:35]
	global_store_dword v249, v245, s[34:35]
	s_add_u32 s6, s2, 0x18000
	s_addc_u32 s7, s3, 0
	global_store_dwordx4 v250, v[76:79], s[6:7] offset:0
	global_store_dwordx4 v250, v[72:75], s[6:7] offset:64
	v_cvt_pk_bf16_f32 v218, v76, v77
	v_cvt_pk_bf16_f32 v219, v78, v79
	v_cvt_pk_bf16_f32 v220, v72, v73
	v_cvt_pk_bf16_f32 v221, v74, v75
	v_cndmask_b32_e64 v222, v218, v219, s[8:9]
	v_cndmask_b32_e64 v223, v220, v221, s[8:9]
	s_nop 0
	v_mov_b32_dpp v222, v222 quad_perm:[1,0,3,2] row_mask:0xf bank_mask:0xf bound_ctrl:1
	v_mov_b32_dpp v223, v223 quad_perm:[1,0,3,2] row_mask:0xf bank_mask:0xf bound_ctrl:1
	v_cndmask_b32_e32 v224, v218, v222, vcc
	v_cndmask_b32_e32 v225, v222, v219, vcc
	v_cndmask_b32_e32 v226, v220, v223, vcc
	v_cndmask_b32_e32 v227, v223, v221, vcc
	v_perm_b32 v228, v225, v224, s10
	v_perm_b32 v229, v225, v224, s11
	v_perm_b32 v230, v227, v226, s10
	v_perm_b32 v231, v227, v226, s11
	s_add_u32 s34, s12, 0x48
	s_addc_u32 s35, s13, 0
	global_store_dword v248, v228, s[34:35]
	global_store_dword v249, v229, s[34:35]
	s_add_u32 s34, s12, 0x2048
	s_addc_u32 s35, s13, 0
	global_store_dword v248, v230, s[34:35]
	global_store_dword v249, v231, s[34:35]
	global_store_dwordx4 v250, v[68:71], s[6:7] offset:512
	global_store_dwordx4 v250, v[64:67], s[6:7] offset:576
	v_cvt_pk_bf16_f32 v232, v68, v69
	v_cvt_pk_bf16_f32 v233, v70, v71
	v_cvt_pk_bf16_f32 v234, v64, v65
	v_cvt_pk_bf16_f32 v235, v66, v67
	v_cndmask_b32_e64 v236, v232, v233, s[8:9]
	v_cndmask_b32_e64 v237, v234, v235, s[8:9]
	s_nop 0
	v_mov_b32_dpp v236, v236 quad_perm:[1,0,3,2] row_mask:0xf bank_mask:0xf bound_ctrl:1
	v_mov_b32_dpp v237, v237 quad_perm:[1,0,3,2] row_mask:0xf bank_mask:0xf bound_ctrl:1
	v_cndmask_b32_e32 v238, v232, v236, vcc
	v_cndmask_b32_e32 v239, v236, v233, vcc
	v_cndmask_b32_e32 v240, v234, v237, vcc
	v_cndmask_b32_e32 v241, v237, v235, vcc
	v_perm_b32 v242, v239, v238, s10
	v_perm_b32 v243, v239, v238, s11
	v_perm_b32 v244, v241, v240, s10
	v_perm_b32 v245, v241, v240, s11
	s_add_u32 s34, s12, 0x10048
	s_addc_u32 s35, s13, 0
	global_store_dword v248, v242, s[34:35]
	global_store_dword v249, v243, s[34:35]
	s_add_u32 s34, s12, 0x12048
	s_addc_u32 s35, s13, 0
	global_store_dword v248, v244, s[34:35]
	global_store_dword v249, v245, s[34:35]
	s_add_u32 s6, s2, 0x40000
	s_addc_u32 s7, s3, 0
	global_store_dwordx4 v250, v[60:63], s[6:7] offset:0
	global_store_dwordx4 v250, v[56:59], s[6:7] offset:64
	v_cvt_pk_bf16_f32 v218, v60, v61
	v_cvt_pk_bf16_f32 v219, v62, v63
	v_cvt_pk_bf16_f32 v220, v56, v57
	v_cvt_pk_bf16_f32 v221, v58, v59
	v_cndmask_b32_e64 v222, v218, v219, s[8:9]
	v_cndmask_b32_e64 v223, v220, v221, s[8:9]
	s_nop 0
	v_mov_b32_dpp v222, v222 quad_perm:[1,0,3,2] row_mask:0xf bank_mask:0xf bound_ctrl:1
	v_mov_b32_dpp v223, v223 quad_perm:[1,0,3,2] row_mask:0xf bank_mask:0xf bound_ctrl:1
	v_cndmask_b32_e32 v224, v218, v222, vcc
	v_cndmask_b32_e32 v225, v222, v219, vcc
	v_cndmask_b32_e32 v226, v220, v223, vcc
	v_cndmask_b32_e32 v227, v223, v221, vcc
	v_perm_b32 v228, v225, v224, s10
	v_perm_b32 v229, v225, v224, s11
	v_perm_b32 v230, v227, v226, s10
	v_perm_b32 v231, v227, v226, s11
	s_add_u32 s34, s12, 0x100
	s_addc_u32 s35, s13, 0
	global_store_dword v248, v228, s[34:35]
	global_store_dword v249, v229, s[34:35]
	s_add_u32 s34, s12, 0x2100
	s_addc_u32 s35, s13, 0
	global_store_dword v248, v230, s[34:35]
	global_store_dword v249, v231, s[34:35]
	global_store_dwordx4 v250, v[52:55], s[6:7] offset:512
	global_store_dwordx4 v250, v[48:51], s[6:7] offset:576
	v_cvt_pk_bf16_f32 v232, v52, v53
	v_cvt_pk_bf16_f32 v233, v54, v55
	v_cvt_pk_bf16_f32 v234, v48, v49
	v_cvt_pk_bf16_f32 v235, v50, v51
	v_cndmask_b32_e64 v236, v232, v233, s[8:9]
	v_cndmask_b32_e64 v237, v234, v235, s[8:9]
	s_nop 0
	v_mov_b32_dpp v236, v236 quad_perm:[1,0,3,2] row_mask:0xf bank_mask:0xf bound_ctrl:1
	v_mov_b32_dpp v237, v237 quad_perm:[1,0,3,2] row_mask:0xf bank_mask:0xf bound_ctrl:1
	v_cndmask_b32_e32 v238, v232, v236, vcc
	v_cndmask_b32_e32 v239, v236, v233, vcc
	v_cndmask_b32_e32 v240, v234, v237, vcc
	v_cndmask_b32_e32 v241, v237, v235, vcc
	v_perm_b32 v242, v239, v238, s10
	v_perm_b32 v243, v239, v238, s11
	v_perm_b32 v244, v241, v240, s10
	v_perm_b32 v245, v241, v240, s11
	s_add_u32 s34, s12, 0x10100
	s_addc_u32 s35, s13, 0
	global_store_dword v248, v242, s[34:35]
	global_store_dword v249, v243, s[34:35]
	s_add_u32 s34, s12, 0x12100
	s_addc_u32 s35, s13, 0
	global_store_dword v248, v244, s[34:35]
	global_store_dword v249, v245, s[34:35]
	s_add_u32 s6, s2, 0x48000
	s_addc_u32 s7, s3, 0
	global_store_dwordx4 v250, v[44:47], s[6:7] offset:0
	global_store_dwordx4 v250, v[40:43], s[6:7] offset:64
	v_cvt_pk_bf16_f32 v218, v44, v45
	v_cvt_pk_bf16_f32 v219, v46, v47
	v_cvt_pk_bf16_f32 v220, v40, v41
	v_cvt_pk_bf16_f32 v221, v42, v43
	v_cndmask_b32_e64 v222, v218, v219, s[8:9]
	v_cndmask_b32_e64 v223, v220, v221, s[8:9]
	s_nop 0
	v_mov_b32_dpp v222, v222 quad_perm:[1,0,3,2] row_mask:0xf bank_mask:0xf bound_ctrl:1
	v_mov_b32_dpp v223, v223 quad_perm:[1,0,3,2] row_mask:0xf bank_mask:0xf bound_ctrl:1
	v_cndmask_b32_e32 v224, v218, v222, vcc
	v_cndmask_b32_e32 v225, v222, v219, vcc
	v_cndmask_b32_e32 v226, v220, v223, vcc
	v_cndmask_b32_e32 v227, v223, v221, vcc
	v_perm_b32 v228, v225, v224, s10
	v_perm_b32 v229, v225, v224, s11
	v_perm_b32 v230, v227, v226, s10
	v_perm_b32 v231, v227, v226, s11
	s_add_u32 s34, s12, 0x108
	s_addc_u32 s35, s13, 0
	global_store_dword v248, v228, s[34:35]
	global_store_dword v249, v229, s[34:35]
	s_add_u32 s34, s12, 0x2108
	s_addc_u32 s35, s13, 0
	global_store_dword v248, v230, s[34:35]
	global_store_dword v249, v231, s[34:35]
	global_store_dwordx4 v250, v[36:39], s[6:7] offset:512
	global_store_dwordx4 v250, v[32:35], s[6:7] offset:576
	v_cvt_pk_bf16_f32 v232, v36, v37
	v_cvt_pk_bf16_f32 v233, v38, v39
	v_cvt_pk_bf16_f32 v234, v32, v33
	v_cvt_pk_bf16_f32 v235, v34, v35
	v_cndmask_b32_e64 v236, v232, v233, s[8:9]
	v_cndmask_b32_e64 v237, v234, v235, s[8:9]
	s_nop 0
	v_mov_b32_dpp v236, v236 quad_perm:[1,0,3,2] row_mask:0xf bank_mask:0xf bound_ctrl:1
	v_mov_b32_dpp v237, v237 quad_perm:[1,0,3,2] row_mask:0xf bank_mask:0xf bound_ctrl:1
	v_cndmask_b32_e32 v238, v232, v236, vcc
	v_cndmask_b32_e32 v239, v236, v233, vcc
	v_cndmask_b32_e32 v240, v234, v237, vcc
	v_cndmask_b32_e32 v241, v237, v235, vcc
	v_perm_b32 v242, v239, v238, s10
	v_perm_b32 v243, v239, v238, s11
	v_perm_b32 v244, v241, v240, s10
	v_perm_b32 v245, v241, v240, s11
	s_add_u32 s34, s12, 0x10108
	s_addc_u32 s35, s13, 0
	global_store_dword v248, v242, s[34:35]
	global_store_dword v249, v243, s[34:35]
	s_add_u32 s34, s12, 0x12108
	s_addc_u32 s35, s13, 0
	global_store_dword v248, v244, s[34:35]
	global_store_dword v249, v245, s[34:35]
	s_add_u32 s6, s2, 0x50000
	s_addc_u32 s7, s3, 0
	global_store_dwordx4 v250, v[28:31], s[6:7] offset:0
	global_store_dwordx4 v250, v[24:27], s[6:7] offset:64
	v_cvt_pk_bf16_f32 v218, v28, v29
	v_cvt_pk_bf16_f32 v219, v30, v31
	v_cvt_pk_bf16_f32 v220, v24, v25
	v_cvt_pk_bf16_f32 v221, v26, v27
	v_cndmask_b32_e64 v222, v218, v219, s[8:9]
	v_cndmask_b32_e64 v223, v220, v221, s[8:9]
	s_nop 0
	v_mov_b32_dpp v222, v222 quad_perm:[1,0,3,2] row_mask:0xf bank_mask:0xf bound_ctrl:1
	v_mov_b32_dpp v223, v223 quad_perm:[1,0,3,2] row_mask:0xf bank_mask:0xf bound_ctrl:1
	v_cndmask_b32_e32 v224, v218, v222, vcc
	v_cndmask_b32_e32 v225, v222, v219, vcc
	v_cndmask_b32_e32 v226, v220, v223, vcc
	v_cndmask_b32_e32 v227, v223, v221, vcc
	v_perm_b32 v228, v225, v224, s10
	v_perm_b32 v229, v225, v224, s11
	v_perm_b32 v230, v227, v226, s10
	v_perm_b32 v231, v227, v226, s11
	s_add_u32 s34, s12, 0x140
	s_addc_u32 s35, s13, 0
	global_store_dword v248, v228, s[34:35]
	global_store_dword v249, v229, s[34:35]
	s_add_u32 s34, s12, 0x2140
	s_addc_u32 s35, s13, 0
	global_store_dword v248, v230, s[34:35]
	global_store_dword v249, v231, s[34:35]
	global_store_dwordx4 v250, v[20:23], s[6:7] offset:512
	global_store_dwordx4 v250, v[16:19], s[6:7] offset:576
	v_cvt_pk_bf16_f32 v232, v20, v21
	v_cvt_pk_bf16_f32 v233, v22, v23
	v_cvt_pk_bf16_f32 v234, v16, v17
	v_cvt_pk_bf16_f32 v235, v18, v19
	v_cndmask_b32_e64 v236, v232, v233, s[8:9]
	v_cndmask_b32_e64 v237, v234, v235, s[8:9]
	s_nop 0
	v_mov_b32_dpp v236, v236 quad_perm:[1,0,3,2] row_mask:0xf bank_mask:0xf bound_ctrl:1
	v_mov_b32_dpp v237, v237 quad_perm:[1,0,3,2] row_mask:0xf bank_mask:0xf bound_ctrl:1
	v_cndmask_b32_e32 v238, v232, v236, vcc
	v_cndmask_b32_e32 v239, v236, v233, vcc
	v_cndmask_b32_e32 v240, v234, v237, vcc
	v_cndmask_b32_e32 v241, v237, v235, vcc
	v_perm_b32 v242, v239, v238, s10
	v_perm_b32 v243, v239, v238, s11
	v_perm_b32 v244, v241, v240, s10
	v_perm_b32 v245, v241, v240, s11
	s_add_u32 s34, s12, 0x10140
	s_addc_u32 s35, s13, 0
	global_store_dword v248, v242, s[34:35]
	global_store_dword v249, v243, s[34:35]
	s_add_u32 s34, s12, 0x12140
	s_addc_u32 s35, s13, 0
	global_store_dword v248, v244, s[34:35]
	global_store_dword v249, v245, s[34:35]
	s_add_u32 s6, s2, 0x58000
	s_addc_u32 s7, s3, 0
	global_store_dwordx4 v250, v[12:15], s[6:7] offset:0
	global_store_dwordx4 v250, v[8:11], s[6:7] offset:64
	v_cvt_pk_bf16_f32 v218, v12, v13
	v_cvt_pk_bf16_f32 v219, v14, v15
	v_cvt_pk_bf16_f32 v220, v8, v9
	v_cvt_pk_bf16_f32 v221, v10, v11
	v_cndmask_b32_e64 v222, v218, v219, s[8:9]
	v_cndmask_b32_e64 v223, v220, v221, s[8:9]
	s_nop 0
	v_mov_b32_dpp v222, v222 quad_perm:[1,0,3,2] row_mask:0xf bank_mask:0xf bound_ctrl:1
	v_mov_b32_dpp v223, v223 quad_perm:[1,0,3,2] row_mask:0xf bank_mask:0xf bound_ctrl:1
	v_cndmask_b32_e32 v224, v218, v222, vcc
	v_cndmask_b32_e32 v225, v222, v219, vcc
	v_cndmask_b32_e32 v226, v220, v223, vcc
	v_cndmask_b32_e32 v227, v223, v221, vcc
	v_perm_b32 v228, v225, v224, s10
	v_perm_b32 v229, v225, v224, s11
	v_perm_b32 v230, v227, v226, s10
	v_perm_b32 v231, v227, v226, s11
	s_add_u32 s34, s12, 0x148
	s_addc_u32 s35, s13, 0
	global_store_dword v248, v228, s[34:35]
	global_store_dword v249, v229, s[34:35]
	s_add_u32 s34, s12, 0x2148
	s_addc_u32 s35, s13, 0
	global_store_dword v248, v230, s[34:35]
	global_store_dword v249, v231, s[34:35]
	global_store_dwordx4 v250, v[4:7], s[6:7] offset:512
	global_store_dwordx4 v250, v[0:3], s[6:7] offset:576
	v_cvt_pk_bf16_f32 v232, v4, v5
	v_cvt_pk_bf16_f32 v233, v6, v7
	v_cvt_pk_bf16_f32 v234, v0, v1
	v_cvt_pk_bf16_f32 v235, v2, v3
	v_cndmask_b32_e64 v236, v232, v233, s[8:9]
	v_cndmask_b32_e64 v237, v234, v235, s[8:9]
	s_nop 0
	v_mov_b32_dpp v236, v236 quad_perm:[1,0,3,2] row_mask:0xf bank_mask:0xf bound_ctrl:1
	v_mov_b32_dpp v237, v237 quad_perm:[1,0,3,2] row_mask:0xf bank_mask:0xf bound_ctrl:1
	v_cndmask_b32_e32 v238, v232, v236, vcc
	v_cndmask_b32_e32 v239, v236, v233, vcc
	v_cndmask_b32_e32 v240, v234, v237, vcc
	v_cndmask_b32_e32 v241, v237, v235, vcc
	v_perm_b32 v242, v239, v238, s10
	v_perm_b32 v243, v239, v238, s11
	v_perm_b32 v244, v241, v240, s10
	v_perm_b32 v245, v241, v240, s11
	s_add_u32 s34, s12, 0x10148
	s_addc_u32 s35, s13, 0
	global_store_dword v248, v242, s[34:35]
	global_store_dword v249, v243, s[34:35]
	s_add_u32 s34, s12, 0x12148
	s_addc_u32 s35, s13, 0
	global_store_dword v248, v244, s[34:35]
	global_store_dword v249, v245, s[34:35]
	s_branch .Lvf_v_end
.Lvf_v_end:
.LBB0_828:
	s_mov_b64 s[8:9], 0
